# P5 epilogue: seam rows of the next (n, ai) group read from LDS one row block ahead
# speedup vs baseline: 1.0024x; 1.0024x over previous
.Lp5_req_skip_n:
	v_cmp_eq_u32_e32 vcc, 0, v223
	s_and_saveexec_b64 s[30:31], vcc
	ds_write_b128 v229, v[48:51] offset:0
	ds_write_b128 v229, v[24:27] offset:16
	ds_write_b128 v229, v[52:55] offset:512
	ds_write_b128 v229, v[28:31] offset:528
	ds_write_b128 v229, v[12:15] offset:4096
	ds_write_b128 v229, v[8:11] offset:4112
	ds_write_b128 v229, v[40:43] offset:4608
	ds_write_b128 v229, v[36:39] offset:4624
	s_mov_b64 exec, s[30:31]
	v_cmp_eq_u32_e32 vcc, 15, v223
	s_and_saveexec_b64 s[30:31], vcc
	ds_write_b128 v229, v[60:63] offset:1024
	ds_write_b128 v229, v[16:19] offset:1040
	ds_write_b128 v229, v[44:47] offset:1536
	ds_write_b128 v229, v[20:23] offset:1552
	ds_write_b128 v229, v[4:7] offset:5120
	ds_write_b128 v229, v[0:3] offset:5136
	ds_write_b128 v229, v[32:35] offset:5632
	ds_write_b128 v229, v[128:131] offset:5648
	s_mov_b64 exec, s[30:31]
	s_waitcnt lgkmcnt(0)
	s_barrier
	s_cmp_eq_u32 s33, 64
	s_cbranch_scc1 .Lp5_edge
	s_cmp_lt_i32 s33, 64
	s_cselect_b32 s9, 11, 14
	s_lshl_b32 s11, 1, s9
	s_add_i32 s11, s11, s28
	s_add_i32 s11, s11, -2
	s_ashr_i32 s11, s11, s9
	s_add_i32 s29, s28, 0xff
	s_ashr_i32 s29, s29, s9
	s_cmp_lt_i32 s29, s11
	s_cbranch_scc0 .Lp5_edge
	ds_read_b128 v[56:59], v231 offset:0
	ds_read_b128 v[132:135], v231 offset:512
	ds_read_b128 v[152:155], v233 offset:0
	ds_read_b128 v[156:159], v233 offset:512
	s_waitcnt lgkmcnt(0)
	v_mov_b32_dpp v56, v60 row_shr:1 row_mask:0xf bank_mask:0xf
	v_mov_b32_dpp v57, v61 row_shr:1 row_mask:0xf bank_mask:0xf
	v_mov_b32_dpp v58, v62 row_shr:1 row_mask:0xf bank_mask:0xf
	v_mov_b32_dpp v59, v63 row_shr:1 row_mask:0xf bank_mask:0xf
	v_mov_b32_dpp v132, v44 row_shr:1 row_mask:0xf bank_mask:0xf
	v_mov_b32_dpp v133, v45 row_shr:1 row_mask:0xf bank_mask:0xf
	v_mov_b32_dpp v134, v46 row_shr:1 row_mask:0xf bank_mask:0xf
	v_mov_b32_dpp v135, v47 row_shr:1 row_mask:0xf bank_mask:0xf
	v_mov_b32_dpp v152, v48 row_shl:1 row_mask:0xf bank_mask:0xf
	v_mov_b32_dpp v153, v49 row_shl:1 row_mask:0xf bank_mask:0xf
	v_mov_b32_dpp v154, v50 row_shl:1 row_mask:0xf bank_mask:0xf
	v_mov_b32_dpp v155, v51 row_shl:1 row_mask:0xf bank_mask:0xf
	v_mov_b32_dpp v156, v52 row_shl:1 row_mask:0xf bank_mask:0xf
	v_mov_b32_dpp v157, v53 row_shl:1 row_mask:0xf bank_mask:0xf
	v_mov_b32_dpp v158, v54 row_shl:1 row_mask:0xf bank_mask:0xf
	v_mov_b32_dpp v159, v55 row_shl:1 row_mask:0xf bank_mask:0xf
	v_pk_fma_f32 v[56:57], v[176:177], v[56:57], v[200:201]
	v_pk_fma_f32 v[58:59], v[178:179], v[58:59], v[202:203]
	v_pk_fma_f32 v[132:133], v[180:181], v[132:133], v[204:205]
	v_pk_fma_f32 v[134:135], v[182:183], v[134:135], v[206:207]
	v_pk_fma_f32 v[56:57], v[48:49], v[184:185], v[56:57]
	v_pk_fma_f32 v[58:59], v[50:51], v[186:187], v[58:59]
	v_pk_fma_f32 v[132:133], v[52:53], v[188:189], v[132:133]
	v_pk_fma_f32 v[134:135], v[54:55], v[190:191], v[134:135]
	v_pk_fma_f32 v[56:57], v[192:193], v[124:125], v[56:57]
	v_pk_fma_f32 v[58:59], v[194:195], v[126:127], v[58:59]
	v_pk_fma_f32 v[132:133], v[196:197], v[116:117], v[132:133]
	v_pk_fma_f32 v[134:135], v[198:199], v[118:119], v[134:135]
	v_and_b32_e32 v212, 0x7fffffff, v56
	v_and_b32_e32 v213, 0x7fffffff, v57
	v_and_b32_e32 v166, 0x7fffffff, v58
	v_and_b32_e32 v167, 0x7fffffff, v59
	v_pk_fma_f32 v[238:239], v[212:213], s[90:91], 1.0 op_sel_hi:[1,0,0]
	v_pk_fma_f32 v[168:169], v[166:167], s[90:91], 1.0 op_sel_hi:[1,0,0]
	v_pk_mul_f32 v[164:165], v[56:57], v[56:57]
	v_pk_mul_f32 v[172:173], v[58:59], v[58:59]
	v_rcp_f32_e32 v238, v238
	v_rcp_f32_e32 v239, v239
	v_rcp_f32_e32 v168, v168
	v_rcp_f32_e32 v169, v169
	v_pk_mul_f32 v[164:165], v[164:165], s[44:45] op_sel_hi:[1,0]
	v_pk_mul_f32 v[172:173], v[172:173], s[44:45] op_sel_hi:[1,0]
	v_pk_fma_f32 v[246:247], v[238:239], s[92:93], v[236:237] op_sel_hi:[1,0,0]
	v_pk_fma_f32 v[170:171], v[168:169], s[92:93], v[236:237] op_sel_hi:[1,0,0]
	v_exp_f32_e32 v164, v164
	v_exp_f32_e32 v165, v165
	v_exp_f32_e32 v172, v172
	v_exp_f32_e32 v173, v173
	v_pk_fma_f32 v[246:247], v[238:239], v[246:247], s[96:97] op_sel_hi:[1,1,0]
	v_pk_fma_f32 v[170:171], v[168:169], v[170:171], s[96:97] op_sel_hi:[1,1,0]
	v_pk_fma_f32 v[246:247], v[238:239], v[246:247], s[0:1] op_sel_hi:[1,1,0]
	v_pk_fma_f32 v[170:171], v[168:169], v[170:171], s[0:1] op_sel_hi:[1,1,0]
	v_pk_fma_f32 v[246:247], v[238:239], v[246:247], s[4:5] op_sel_hi:[1,1,0]
	v_pk_fma_f32 v[170:171], v[168:169], v[170:171], s[4:5] op_sel_hi:[1,1,0]
	v_pk_mul_f32 v[246:247], v[238:239], v[246:247]
	v_pk_mul_f32 v[170:171], v[168:169], v[170:171]
	v_max_f32_e32 v238, 0, v56
	v_max_f32_e32 v239, 0, v57
	v_max_f32_e32 v168, 0, v58
	v_max_f32_e32 v169, 0, v59
	v_pk_mul_f32 v[246:247], v[164:165], v[246:247]
	v_pk_mul_f32 v[170:171], v[172:173], v[170:171]
	v_pk_fma_f32 v[164:165], v[212:213], v[246:247], v[238:239] neg_lo:[1,0,0] neg_hi:[1,0,0]
	v_pk_fma_f32 v[172:173], v[166:167], v[170:171], v[168:169] neg_lo:[1,0,0] neg_hi:[1,0,0]
	v_pk_mul_f32 v[246:247], v[164:165], v[132:133]
	v_pk_mul_f32 v[170:171], v[172:173], v[134:135]
	v_cvt_pk_bf16_f32 v160, v246, v247
	v_cvt_pk_bf16_f32 v161, v170, v171
	v_pk_fma_f32 v[48:49], v[176:177], v[48:49], v[200:201]
	v_pk_fma_f32 v[50:51], v[178:179], v[50:51], v[202:203]
	v_pk_fma_f32 v[52:53], v[180:181], v[52:53], v[204:205]
	v_pk_fma_f32 v[54:55], v[182:183], v[54:55], v[206:207]
	v_pk_fma_f32 v[48:49], v[124:125], v[184:185], v[48:49]
	v_pk_fma_f32 v[50:51], v[126:127], v[186:187], v[50:51]
	v_pk_fma_f32 v[52:53], v[116:117], v[188:189], v[52:53]
	v_pk_fma_f32 v[54:55], v[118:119], v[190:191], v[54:55]
	v_pk_fma_f32 v[48:49], v[192:193], v[112:113], v[48:49]
	v_pk_fma_f32 v[50:51], v[194:195], v[114:115], v[50:51]
	v_pk_fma_f32 v[52:53], v[196:197], v[100:101], v[52:53]
	v_pk_fma_f32 v[54:55], v[198:199], v[102:103], v[54:55]
	v_and_b32_e32 v212, 0x7fffffff, v48
	v_and_b32_e32 v213, 0x7fffffff, v49
	v_and_b32_e32 v134, 0x7fffffff, v50
	v_and_b32_e32 v135, 0x7fffffff, v51
	v_pk_fma_f32 v[238:239], v[212:213], s[90:91], 1.0 op_sel_hi:[1,0,0]
	v_pk_fma_f32 v[164:165], v[134:135], s[90:91], 1.0 op_sel_hi:[1,0,0]
	v_pk_mul_f32 v[132:133], v[48:49], v[48:49]
	v_pk_mul_f32 v[168:169], v[50:51], v[50:51]
	v_rcp_f32_e32 v238, v238
	v_rcp_f32_e32 v239, v239
	v_rcp_f32_e32 v164, v164
	v_rcp_f32_e32 v165, v165
	v_pk_mul_f32 v[132:133], v[132:133], s[44:45] op_sel_hi:[1,0]
	v_pk_mul_f32 v[168:169], v[168:169], s[44:45] op_sel_hi:[1,0]
	v_pk_fma_f32 v[246:247], v[238:239], s[92:93], v[236:237] op_sel_hi:[1,0,0]
	v_pk_fma_f32 v[166:167], v[164:165], s[92:93], v[236:237] op_sel_hi:[1,0,0]
	v_exp_f32_e32 v132, v132
	v_exp_f32_e32 v133, v133
	v_exp_f32_e32 v168, v168
	v_exp_f32_e32 v169, v169
	v_pk_fma_f32 v[246:247], v[238:239], v[246:247], s[96:97] op_sel_hi:[1,1,0]
	v_pk_fma_f32 v[166:167], v[164:165], v[166:167], s[96:97] op_sel_hi:[1,1,0]
	v_pk_fma_f32 v[246:247], v[238:239], v[246:247], s[0:1] op_sel_hi:[1,1,0]
	v_pk_fma_f32 v[166:167], v[164:165], v[166:167], s[0:1] op_sel_hi:[1,1,0]
	v_pk_fma_f32 v[246:247], v[238:239], v[246:247], s[4:5] op_sel_hi:[1,1,0]
	v_pk_fma_f32 v[166:167], v[164:165], v[166:167], s[4:5] op_sel_hi:[1,1,0]
	v_pk_mul_f32 v[246:247], v[238:239], v[246:247]
	v_pk_mul_f32 v[166:167], v[164:165], v[166:167]
	v_max_f32_e32 v238, 0, v48
	v_max_f32_e32 v239, 0, v49
	v_max_f32_e32 v164, 0, v50
	v_max_f32_e32 v165, 0, v51
	v_pk_mul_f32 v[246:247], v[132:133], v[246:247]
	v_pk_mul_f32 v[166:167], v[168:169], v[166:167]
	v_pk_fma_f32 v[132:133], v[212:213], v[246:247], v[238:239] neg_lo:[1,0,0] neg_hi:[1,0,0]
	v_pk_fma_f32 v[168:169], v[134:135], v[166:167], v[164:165] neg_lo:[1,0,0] neg_hi:[1,0,0]
	v_pk_mul_f32 v[246:247], v[132:133], v[52:53]
	v_pk_mul_f32 v[166:167], v[168:169], v[54:55]
	v_cvt_pk_bf16_f32 v56, v246, v247
	v_cvt_pk_bf16_f32 v57, v166, v167
	v_pk_fma_f32 v[124:125], v[176:177], v[124:125], v[200:201]
	v_pk_fma_f32 v[126:127], v[178:179], v[126:127], v[202:203]
	v_pk_fma_f32 v[116:117], v[180:181], v[116:117], v[204:205]
	v_pk_fma_f32 v[118:119], v[182:183], v[118:119], v[206:207]
	v_pk_fma_f32 v[124:125], v[112:113], v[184:185], v[124:125]
	v_pk_fma_f32 v[126:127], v[114:115], v[186:187], v[126:127]
	v_pk_fma_f32 v[116:117], v[100:101], v[188:189], v[116:117]
	v_pk_fma_f32 v[118:119], v[102:103], v[190:191], v[118:119]
	v_pk_fma_f32 v[124:125], v[192:193], v[60:61], v[124:125]
	v_pk_fma_f32 v[126:127], v[194:195], v[62:63], v[126:127]
	v_pk_fma_f32 v[116:117], v[196:197], v[44:45], v[116:117]
	v_pk_fma_f32 v[118:119], v[198:199], v[46:47], v[118:119]
	v_and_b32_e32 v212, 0x7fffffff, v124
	v_and_b32_e32 v213, 0x7fffffff, v125
	v_and_b32_e32 v54, 0x7fffffff, v126
	v_and_b32_e32 v55, 0x7fffffff, v127
	v_pk_fma_f32 v[238:239], v[212:213], s[90:91], 1.0 op_sel_hi:[1,0,0]
	v_pk_fma_f32 v[132:133], v[54:55], s[90:91], 1.0 op_sel_hi:[1,0,0]
	v_pk_mul_f32 v[52:53], v[124:125], v[124:125]
	v_pk_mul_f32 v[164:165], v[126:127], v[126:127]
	v_rcp_f32_e32 v238, v238
	v_rcp_f32_e32 v239, v239
	v_rcp_f32_e32 v132, v132
	v_rcp_f32_e32 v133, v133
	v_pk_mul_f32 v[52:53], v[52:53], s[44:45] op_sel_hi:[1,0]
	v_pk_mul_f32 v[164:165], v[164:165], s[44:45] op_sel_hi:[1,0]
	v_pk_fma_f32 v[246:247], v[238:239], s[92:93], v[236:237] op_sel_hi:[1,0,0]
	v_pk_fma_f32 v[134:135], v[132:133], s[92:93], v[236:237] op_sel_hi:[1,0,0]
	v_exp_f32_e32 v52, v52
	v_exp_f32_e32 v53, v53
	v_exp_f32_e32 v164, v164
	v_exp_f32_e32 v165, v165
	v_pk_fma_f32 v[246:247], v[238:239], v[246:247], s[96:97] op_sel_hi:[1,1,0]
	v_pk_fma_f32 v[134:135], v[132:133], v[134:135], s[96:97] op_sel_hi:[1,1,0]
	v_pk_fma_f32 v[246:247], v[238:239], v[246:247], s[0:1] op_sel_hi:[1,1,0]
	v_pk_fma_f32 v[134:135], v[132:133], v[134:135], s[0:1] op_sel_hi:[1,1,0]
	v_pk_fma_f32 v[246:247], v[238:239], v[246:247], s[4:5] op_sel_hi:[1,1,0]
	v_pk_fma_f32 v[134:135], v[132:133], v[134:135], s[4:5] op_sel_hi:[1,1,0]
	v_pk_mul_f32 v[246:247], v[238:239], v[246:247]
	v_pk_mul_f32 v[134:135], v[132:133], v[134:135]
	v_max_f32_e32 v238, 0, v124
	v_max_f32_e32 v239, 0, v125
	v_max_f32_e32 v132, 0, v126
	v_max_f32_e32 v133, 0, v127
	v_pk_mul_f32 v[246:247], v[52:53], v[246:247]
	v_pk_mul_f32 v[134:135], v[164:165], v[134:135]
	v_pk_fma_f32 v[52:53], v[212:213], v[246:247], v[238:239] neg_lo:[1,0,0] neg_hi:[1,0,0]
	v_pk_fma_f32 v[164:165], v[54:55], v[134:135], v[132:133] neg_lo:[1,0,0] neg_hi:[1,0,0]
	v_pk_mul_f32 v[246:247], v[52:53], v[116:117]
	v_pk_mul_f32 v[134:135], v[164:165], v[118:119]
	v_cvt_pk_bf16_f32 v48, v246, v247
	v_cvt_pk_bf16_f32 v49, v134, v135
	v_pk_fma_f32 v[112:113], v[176:177], v[112:113], v[200:201]
	v_pk_fma_f32 v[114:115], v[178:179], v[114:115], v[202:203]
	v_pk_fma_f32 v[100:101], v[180:181], v[100:101], v[204:205]
	v_pk_fma_f32 v[102:103], v[182:183], v[102:103], v[206:207]
	v_pk_fma_f32 v[112:113], v[60:61], v[184:185], v[112:113]
	v_pk_fma_f32 v[114:115], v[62:63], v[186:187], v[114:115]
	v_pk_fma_f32 v[100:101], v[44:45], v[188:189], v[100:101]
	v_pk_fma_f32 v[102:103], v[46:47], v[190:191], v[102:103]
	v_pk_fma_f32 v[112:113], v[192:193], v[152:153], v[112:113]
	v_pk_fma_f32 v[114:115], v[194:195], v[154:155], v[114:115]
	v_pk_fma_f32 v[100:101], v[196:197], v[156:157], v[100:101]
	v_pk_fma_f32 v[102:103], v[198:199], v[158:159], v[102:103]
	v_and_b32_e32 v212, 0x7fffffff, v112
	v_and_b32_e32 v213, 0x7fffffff, v113
	v_and_b32_e32 v118, 0x7fffffff, v114
	v_and_b32_e32 v119, 0x7fffffff, v115
	v_pk_fma_f32 v[238:239], v[212:213], s[90:91], 1.0 op_sel_hi:[1,0,0]
	v_pk_fma_f32 v[124:125], v[118:119], s[90:91], 1.0 op_sel_hi:[1,0,0]
	v_pk_mul_f32 v[116:117], v[112:113], v[112:113]
	v_pk_mul_f32 v[132:133], v[114:115], v[114:115]
	v_rcp_f32_e32 v238, v238
	v_rcp_f32_e32 v239, v239
	v_rcp_f32_e32 v124, v124
	v_rcp_f32_e32 v125, v125
	v_pk_mul_f32 v[116:117], v[116:117], s[44:45] op_sel_hi:[1,0]
	v_pk_mul_f32 v[132:133], v[132:133], s[44:45] op_sel_hi:[1,0]
	v_pk_fma_f32 v[246:247], v[238:239], s[92:93], v[236:237] op_sel_hi:[1,0,0]
	v_pk_fma_f32 v[126:127], v[124:125], s[92:93], v[236:237] op_sel_hi:[1,0,0]
	v_exp_f32_e32 v116, v116
	v_exp_f32_e32 v117, v117
	v_exp_f32_e32 v132, v132
	v_exp_f32_e32 v133, v133
	v_pk_fma_f32 v[246:247], v[238:239], v[246:247], s[96:97] op_sel_hi:[1,1,0]
	v_pk_fma_f32 v[126:127], v[124:125], v[126:127], s[96:97] op_sel_hi:[1,1,0]
	v_pk_fma_f32 v[246:247], v[238:239], v[246:247], s[0:1] op_sel_hi:[1,1,0]
	v_pk_fma_f32 v[126:127], v[124:125], v[126:127], s[0:1] op_sel_hi:[1,1,0]
	v_pk_fma_f32 v[246:247], v[238:239], v[246:247], s[4:5] op_sel_hi:[1,1,0]
	v_pk_fma_f32 v[126:127], v[124:125], v[126:127], s[4:5] op_sel_hi:[1,1,0]
	v_pk_mul_f32 v[246:247], v[238:239], v[246:247]
	v_pk_mul_f32 v[126:127], v[124:125], v[126:127]
	v_max_f32_e32 v238, 0, v112
	v_max_f32_e32 v239, 0, v113
	v_max_f32_e32 v124, 0, v114
	v_max_f32_e32 v125, 0, v115
	v_pk_mul_f32 v[246:247], v[116:117], v[246:247]
	v_pk_mul_f32 v[126:127], v[132:133], v[126:127]
	v_pk_fma_f32 v[116:117], v[212:213], v[246:247], v[238:239] neg_lo:[1,0,0] neg_hi:[1,0,0]
	v_pk_fma_f32 v[132:133], v[118:119], v[126:127], v[124:125] neg_lo:[1,0,0] neg_hi:[1,0,0]
	v_pk_mul_f32 v[246:247], v[116:117], v[100:101]
	v_pk_mul_f32 v[126:127], v[132:133], v[102:103]
	v_cvt_pk_bf16_f32 v52, v246, v247
	v_cvt_pk_bf16_f32 v53, v126, v127
	ds_read_b128 v[44:47], v232 offset:0
	ds_read_b128 v[60:63], v232 offset:512
	ds_read_b128 v[100:103], v234 offset:0
	ds_read_b128 v[112:115], v234 offset:512
	s_waitcnt lgkmcnt(0)
	v_mov_b32_dpp v44, v4 row_shr:1 row_mask:0xf bank_mask:0xf
	v_mov_b32_dpp v45, v5 row_shr:1 row_mask:0xf bank_mask:0xf
	v_mov_b32_dpp v46, v6 row_shr:1 row_mask:0xf bank_mask:0xf
	v_mov_b32_dpp v47, v7 row_shr:1 row_mask:0xf bank_mask:0xf
	v_mov_b32_dpp v60, v32 row_shr:1 row_mask:0xf bank_mask:0xf
	v_mov_b32_dpp v61, v33 row_shr:1 row_mask:0xf bank_mask:0xf
	v_mov_b32_dpp v62, v34 row_shr:1 row_mask:0xf bank_mask:0xf
	v_mov_b32_dpp v63, v35 row_shr:1 row_mask:0xf bank_mask:0xf
	v_mov_b32_dpp v100, v12 row_shl:1 row_mask:0xf bank_mask:0xf
	v_mov_b32_dpp v101, v13 row_shl:1 row_mask:0xf bank_mask:0xf
	v_mov_b32_dpp v102, v14 row_shl:1 row_mask:0xf bank_mask:0xf
	v_mov_b32_dpp v103, v15 row_shl:1 row_mask:0xf bank_mask:0xf
	v_mov_b32_dpp v112, v40 row_shl:1 row_mask:0xf bank_mask:0xf
	v_mov_b32_dpp v113, v41 row_shl:1 row_mask:0xf bank_mask:0xf
	v_mov_b32_dpp v114, v42 row_shl:1 row_mask:0xf bank_mask:0xf
	v_mov_b32_dpp v115, v43 row_shl:1 row_mask:0xf bank_mask:0xf
	v_pk_fma_f32 v[44:45], v[176:177], v[44:45], v[200:201]
	v_pk_fma_f32 v[46:47], v[178:179], v[46:47], v[202:203]
	v_pk_fma_f32 v[60:61], v[180:181], v[60:61], v[204:205]
	v_pk_fma_f32 v[62:63], v[182:183], v[62:63], v[206:207]
	v_pk_fma_f32 v[44:45], v[12:13], v[184:185], v[44:45]
	v_pk_fma_f32 v[46:47], v[14:15], v[186:187], v[46:47]
	v_pk_fma_f32 v[60:61], v[40:41], v[188:189], v[60:61]
	v_pk_fma_f32 v[62:63], v[42:43], v[190:191], v[62:63]
	v_pk_fma_f32 v[44:45], v[192:193], v[92:93], v[44:45]
	v_pk_fma_f32 v[46:47], v[194:195], v[94:95], v[46:47]
	v_pk_fma_f32 v[60:61], v[196:197], v[84:85], v[60:61]
	v_pk_fma_f32 v[62:63], v[198:199], v[86:87], v[62:63]
	v_and_b32_e32 v212, 0x7fffffff, v44
	v_and_b32_e32 v213, 0x7fffffff, v45
	v_and_b32_e32 v126, 0x7fffffff, v46
	v_and_b32_e32 v127, 0x7fffffff, v47
	v_pk_fma_f32 v[238:239], v[212:213], s[90:91], 1.0 op_sel_hi:[1,0,0]
	v_pk_fma_f32 v[132:133], v[126:127], s[90:91], 1.0 op_sel_hi:[1,0,0]
	v_pk_mul_f32 v[124:125], v[44:45], v[44:45]
	v_pk_mul_f32 v[152:153], v[46:47], v[46:47]
	v_rcp_f32_e32 v238, v238
	v_rcp_f32_e32 v239, v239
	v_rcp_f32_e32 v132, v132
	v_rcp_f32_e32 v133, v133
	v_pk_mul_f32 v[124:125], v[124:125], s[44:45] op_sel_hi:[1,0]
	v_pk_mul_f32 v[152:153], v[152:153], s[44:45] op_sel_hi:[1,0]
	v_pk_fma_f32 v[246:247], v[238:239], s[92:93], v[236:237] op_sel_hi:[1,0,0]
	v_pk_fma_f32 v[134:135], v[132:133], s[92:93], v[236:237] op_sel_hi:[1,0,0]
	v_exp_f32_e32 v124, v124
	v_exp_f32_e32 v125, v125
	v_exp_f32_e32 v152, v152
	v_exp_f32_e32 v153, v153
	v_pk_fma_f32 v[246:247], v[238:239], v[246:247], s[96:97] op_sel_hi:[1,1,0]
	v_pk_fma_f32 v[134:135], v[132:133], v[134:135], s[96:97] op_sel_hi:[1,1,0]
	v_pk_fma_f32 v[246:247], v[238:239], v[246:247], s[0:1] op_sel_hi:[1,1,0]
	v_pk_fma_f32 v[134:135], v[132:133], v[134:135], s[0:1] op_sel_hi:[1,1,0]
	v_pk_fma_f32 v[246:247], v[238:239], v[246:247], s[4:5] op_sel_hi:[1,1,0]
	v_pk_fma_f32 v[134:135], v[132:133], v[134:135], s[4:5] op_sel_hi:[1,1,0]
	v_pk_mul_f32 v[246:247], v[238:239], v[246:247]
	v_pk_mul_f32 v[134:135], v[132:133], v[134:135]
	v_max_f32_e32 v238, 0, v44
	v_max_f32_e32 v239, 0, v45
	v_max_f32_e32 v132, 0, v46
	v_max_f32_e32 v133, 0, v47
	v_pk_mul_f32 v[246:247], v[124:125], v[246:247]
	v_pk_mul_f32 v[134:135], v[152:153], v[134:135]
	v_pk_fma_f32 v[124:125], v[212:213], v[246:247], v[238:239] neg_lo:[1,0,0] neg_hi:[1,0,0]
	v_pk_fma_f32 v[152:153], v[126:127], v[134:135], v[132:133] neg_lo:[1,0,0] neg_hi:[1,0,0]
	v_pk_mul_f32 v[246:247], v[124:125], v[60:61]
	v_pk_mul_f32 v[134:135], v[152:153], v[62:63]
	v_cvt_pk_bf16_f32 v116, v246, v247
	v_cvt_pk_bf16_f32 v117, v134, v135
	v_pk_fma_f32 v[12:13], v[176:177], v[12:13], v[200:201]
	v_pk_fma_f32 v[14:15], v[178:179], v[14:15], v[202:203]
	v_pk_fma_f32 v[40:41], v[180:181], v[40:41], v[204:205]
	v_pk_fma_f32 v[42:43], v[182:183], v[42:43], v[206:207]
	v_pk_fma_f32 v[12:13], v[92:93], v[184:185], v[12:13]
	v_pk_fma_f32 v[14:15], v[94:95], v[186:187], v[14:15]
	v_pk_fma_f32 v[40:41], v[84:85], v[188:189], v[40:41]
	v_pk_fma_f32 v[42:43], v[86:87], v[190:191], v[42:43]
	v_pk_fma_f32 v[12:13], v[192:193], v[80:81], v[12:13]
	v_pk_fma_f32 v[14:15], v[194:195], v[82:83], v[14:15]
	v_pk_fma_f32 v[40:41], v[196:197], v[68:69], v[40:41]
	v_pk_fma_f32 v[42:43], v[198:199], v[70:71], v[42:43]
	v_and_b32_e32 v212, 0x7fffffff, v12
	v_and_b32_e32 v213, 0x7fffffff, v13
	v_and_b32_e32 v62, 0x7fffffff, v14
	v_and_b32_e32 v63, 0x7fffffff, v15
	v_pk_fma_f32 v[238:239], v[212:213], s[90:91], 1.0 op_sel_hi:[1,0,0]
	v_pk_fma_f32 v[124:125], v[62:63], s[90:91], 1.0 op_sel_hi:[1,0,0]
	v_pk_mul_f32 v[60:61], v[12:13], v[12:13]
	v_pk_mul_f32 v[132:133], v[14:15], v[14:15]
	v_rcp_f32_e32 v238, v238
	v_rcp_f32_e32 v239, v239
	v_rcp_f32_e32 v124, v124
	v_rcp_f32_e32 v125, v125
	v_pk_mul_f32 v[60:61], v[60:61], s[44:45] op_sel_hi:[1,0]
	v_pk_mul_f32 v[132:133], v[132:133], s[44:45] op_sel_hi:[1,0]
	v_pk_fma_f32 v[246:247], v[238:239], s[92:93], v[236:237] op_sel_hi:[1,0,0]
	v_pk_fma_f32 v[126:127], v[124:125], s[92:93], v[236:237] op_sel_hi:[1,0,0]
	v_exp_f32_e32 v60, v60
	v_exp_f32_e32 v61, v61
	v_exp_f32_e32 v132, v132
	v_exp_f32_e32 v133, v133
	v_pk_fma_f32 v[246:247], v[238:239], v[246:247], s[96:97] op_sel_hi:[1,1,0]
	v_pk_fma_f32 v[126:127], v[124:125], v[126:127], s[96:97] op_sel_hi:[1,1,0]
	v_pk_fma_f32 v[246:247], v[238:239], v[246:247], s[0:1] op_sel_hi:[1,1,0]
	v_pk_fma_f32 v[126:127], v[124:125], v[126:127], s[0:1] op_sel_hi:[1,1,0]
	v_pk_fma_f32 v[246:247], v[238:239], v[246:247], s[4:5] op_sel_hi:[1,1,0]
	v_pk_fma_f32 v[126:127], v[124:125], v[126:127], s[4:5] op_sel_hi:[1,1,0]
	v_pk_mul_f32 v[246:247], v[238:239], v[246:247]
	v_pk_mul_f32 v[126:127], v[124:125], v[126:127]
	v_max_f32_e32 v238, 0, v12
	v_max_f32_e32 v239, 0, v13
	v_max_f32_e32 v124, 0, v14
	v_max_f32_e32 v125, 0, v15
	v_pk_mul_f32 v[246:247], v[60:61], v[246:247]
	v_pk_mul_f32 v[126:127], v[132:133], v[126:127]
	v_pk_fma_f32 v[60:61], v[212:213], v[246:247], v[238:239] neg_lo:[1,0,0] neg_hi:[1,0,0]
	v_pk_fma_f32 v[132:133], v[62:63], v[126:127], v[124:125] neg_lo:[1,0,0] neg_hi:[1,0,0]
	v_pk_mul_f32 v[246:247], v[60:61], v[40:41]
	v_pk_mul_f32 v[126:127], v[132:133], v[42:43]
	v_cvt_pk_bf16_f32 v44, v246, v247
	v_cvt_pk_bf16_f32 v45, v126, v127
	v_pk_fma_f32 v[92:93], v[176:177], v[92:93], v[200:201]
	v_pk_fma_f32 v[94:95], v[178:179], v[94:95], v[202:203]
	v_pk_fma_f32 v[84:85], v[180:181], v[84:85], v[204:205]
	v_pk_fma_f32 v[86:87], v[182:183], v[86:87], v[206:207]
	v_pk_fma_f32 v[92:93], v[80:81], v[184:185], v[92:93]
	v_pk_fma_f32 v[94:95], v[82:83], v[186:187], v[94:95]
	v_pk_fma_f32 v[84:85], v[68:69], v[188:189], v[84:85]
	v_pk_fma_f32 v[86:87], v[70:71], v[190:191], v[86:87]
	v_pk_fma_f32 v[92:93], v[192:193], v[4:5], v[92:93]
	v_pk_fma_f32 v[94:95], v[194:195], v[6:7], v[94:95]
	v_pk_fma_f32 v[84:85], v[196:197], v[32:33], v[84:85]
	v_pk_fma_f32 v[86:87], v[198:199], v[34:35], v[86:87]
	ds_read_b128 v[12:15], v231 offset:16
	ds_read_b128 v[40:43], v231 offset:528
	ds_read_b128 v[60:63], v233 offset:16
	ds_read_b128 v[124:127], v233 offset:528
	v_and_b32_e32 v212, 0x7fffffff, v92
	v_and_b32_e32 v213, 0x7fffffff, v93
	v_and_b32_e32 v154, 0x7fffffff, v94
	v_and_b32_e32 v155, 0x7fffffff, v95
	v_pk_fma_f32 v[238:239], v[212:213], s[90:91], 1.0 op_sel_hi:[1,0,0]
	v_pk_fma_f32 v[156:157], v[154:155], s[90:91], 1.0 op_sel_hi:[1,0,0]
	v_pk_mul_f32 v[152:153], v[92:93], v[92:93]
	v_pk_mul_f32 v[164:165], v[94:95], v[94:95]
	v_rcp_f32_e32 v238, v238
	v_rcp_f32_e32 v239, v239
	v_rcp_f32_e32 v156, v156
	v_rcp_f32_e32 v157, v157
	v_pk_mul_f32 v[152:153], v[152:153], s[44:45] op_sel_hi:[1,0]
	v_pk_mul_f32 v[164:165], v[164:165], s[44:45] op_sel_hi:[1,0]
	v_pk_fma_f32 v[246:247], v[238:239], s[92:93], v[236:237] op_sel_hi:[1,0,0]
	v_pk_fma_f32 v[158:159], v[156:157], s[92:93], v[236:237] op_sel_hi:[1,0,0]
	v_exp_f32_e32 v152, v152
	v_exp_f32_e32 v153, v153
	v_exp_f32_e32 v164, v164
	v_exp_f32_e32 v165, v165
	v_pk_fma_f32 v[246:247], v[238:239], v[246:247], s[96:97] op_sel_hi:[1,1,0]
	v_pk_fma_f32 v[158:159], v[156:157], v[158:159], s[96:97] op_sel_hi:[1,1,0]
	v_pk_fma_f32 v[246:247], v[238:239], v[246:247], s[0:1] op_sel_hi:[1,1,0]
	v_pk_fma_f32 v[158:159], v[156:157], v[158:159], s[0:1] op_sel_hi:[1,1,0]
	v_pk_fma_f32 v[246:247], v[238:239], v[246:247], s[4:5] op_sel_hi:[1,1,0]
	v_pk_fma_f32 v[158:159], v[156:157], v[158:159], s[4:5] op_sel_hi:[1,1,0]
	v_pk_mul_f32 v[246:247], v[238:239], v[246:247]
	v_pk_mul_f32 v[158:159], v[156:157], v[158:159]
	v_max_f32_e32 v238, 0, v92
	v_max_f32_e32 v239, 0, v93
	v_max_f32_e32 v156, 0, v94
	v_max_f32_e32 v157, 0, v95
	v_pk_mul_f32 v[246:247], v[152:153], v[246:247]
	v_pk_mul_f32 v[158:159], v[164:165], v[158:159]
	v_pk_fma_f32 v[152:153], v[212:213], v[246:247], v[238:239] neg_lo:[1,0,0] neg_hi:[1,0,0]
	v_pk_fma_f32 v[164:165], v[154:155], v[158:159], v[156:157] neg_lo:[1,0,0] neg_hi:[1,0,0]
	v_pk_mul_f32 v[246:247], v[152:153], v[84:85]
	v_pk_mul_f32 v[158:159], v[164:165], v[86:87]
	v_cvt_pk_bf16_f32 v132, v246, v247
	v_cvt_pk_bf16_f32 v133, v158, v159
	v_pk_fma_f32 v[80:81], v[176:177], v[80:81], v[200:201]
	v_pk_fma_f32 v[82:83], v[178:179], v[82:83], v[202:203]
	v_pk_fma_f32 v[68:69], v[180:181], v[68:69], v[204:205]
	v_pk_fma_f32 v[70:71], v[182:183], v[70:71], v[206:207]
	v_pk_fma_f32 v[80:81], v[4:5], v[184:185], v[80:81]
	v_pk_fma_f32 v[82:83], v[6:7], v[186:187], v[82:83]
	v_pk_fma_f32 v[68:69], v[32:33], v[188:189], v[68:69]
	v_pk_fma_f32 v[70:71], v[34:35], v[190:191], v[70:71]
	v_pk_fma_f32 v[80:81], v[192:193], v[100:101], v[80:81]
	v_pk_fma_f32 v[82:83], v[194:195], v[102:103], v[82:83]
	v_pk_fma_f32 v[68:69], v[196:197], v[112:113], v[68:69]
	v_pk_fma_f32 v[70:71], v[198:199], v[114:115], v[70:71]
	v_and_b32_e32 v212, 0x7fffffff, v80
	v_and_b32_e32 v213, 0x7fffffff, v81
	v_and_b32_e32 v94, 0x7fffffff, v82
	v_and_b32_e32 v95, 0x7fffffff, v83
	v_pk_fma_f32 v[238:239], v[212:213], s[90:91], 1.0 op_sel_hi:[1,0,0]
	v_pk_fma_f32 v[152:153], v[94:95], s[90:91], 1.0 op_sel_hi:[1,0,0]
	v_pk_mul_f32 v[92:93], v[80:81], v[80:81]
	v_pk_mul_f32 v[156:157], v[82:83], v[82:83]
	v_rcp_f32_e32 v238, v238
	v_rcp_f32_e32 v239, v239
	v_rcp_f32_e32 v152, v152
	v_rcp_f32_e32 v153, v153
	v_pk_mul_f32 v[92:93], v[92:93], s[44:45] op_sel_hi:[1,0]
	v_pk_mul_f32 v[156:157], v[156:157], s[44:45] op_sel_hi:[1,0]
	v_pk_fma_f32 v[246:247], v[238:239], s[92:93], v[236:237] op_sel_hi:[1,0,0]
	v_pk_fma_f32 v[154:155], v[152:153], s[92:93], v[236:237] op_sel_hi:[1,0,0]
	v_exp_f32_e32 v92, v92
	v_exp_f32_e32 v93, v93
	v_exp_f32_e32 v156, v156
	v_exp_f32_e32 v157, v157
	v_pk_fma_f32 v[246:247], v[238:239], v[246:247], s[96:97] op_sel_hi:[1,1,0]
	v_pk_fma_f32 v[154:155], v[152:153], v[154:155], s[96:97] op_sel_hi:[1,1,0]
	v_pk_fma_f32 v[246:247], v[238:239], v[246:247], s[0:1] op_sel_hi:[1,1,0]
	v_pk_fma_f32 v[154:155], v[152:153], v[154:155], s[0:1] op_sel_hi:[1,1,0]
	v_pk_fma_f32 v[246:247], v[238:239], v[246:247], s[4:5] op_sel_hi:[1,1,0]
	v_pk_fma_f32 v[154:155], v[152:153], v[154:155], s[4:5] op_sel_hi:[1,1,0]
	v_pk_mul_f32 v[246:247], v[238:239], v[246:247]
	v_pk_mul_f32 v[154:155], v[152:153], v[154:155]
	v_max_f32_e32 v238, 0, v80
	v_max_f32_e32 v239, 0, v81
	v_max_f32_e32 v152, 0, v82
	v_max_f32_e32 v153, 0, v83
	v_pk_mul_f32 v[246:247], v[92:93], v[246:247]
	v_pk_mul_f32 v[154:155], v[156:157], v[154:155]
	v_pk_fma_f32 v[92:93], v[212:213], v[246:247], v[238:239] neg_lo:[1,0,0] neg_hi:[1,0,0]
	v_pk_fma_f32 v[156:157], v[94:95], v[154:155], v[152:153] neg_lo:[1,0,0] neg_hi:[1,0,0]
	v_pk_mul_f32 v[246:247], v[92:93], v[68:69]
	v_pk_mul_f32 v[154:155], v[156:157], v[70:71]
	v_cvt_pk_bf16_f32 v84, v246, v247
	v_cvt_pk_bf16_f32 v85, v154, v155
	ds_read_b128 v[4:7], v226 offset:16
	ds_read_b128 v[32:35], v226 offset:528
	ds_read_b128 v[68:71], v226 offset:1040
	ds_read_b128 v[80:83], v226 offset:1552
	ds_read_b128 v[92:95], v226 offset:2064
	ds_read_b128 v[100:103], v226 offset:2576
	ds_read_b128 v[112:115], v226 offset:3088
	ds_read_b128 v[152:155], v226 offset:3600
	s_waitcnt lgkmcnt(0)
	v_mov_b32_dpp v12, v16 row_shr:1 row_mask:0xf bank_mask:0xf
	v_mov_b32_dpp v13, v17 row_shr:1 row_mask:0xf bank_mask:0xf
	v_mov_b32_dpp v14, v18 row_shr:1 row_mask:0xf bank_mask:0xf
	v_mov_b32_dpp v15, v19 row_shr:1 row_mask:0xf bank_mask:0xf
	v_mov_b32_dpp v40, v20 row_shr:1 row_mask:0xf bank_mask:0xf
	v_mov_b32_dpp v41, v21 row_shr:1 row_mask:0xf bank_mask:0xf
	v_mov_b32_dpp v42, v22 row_shr:1 row_mask:0xf bank_mask:0xf
	v_mov_b32_dpp v43, v23 row_shr:1 row_mask:0xf bank_mask:0xf
	v_mov_b32_dpp v60, v24 row_shl:1 row_mask:0xf bank_mask:0xf
	v_mov_b32_dpp v61, v25 row_shl:1 row_mask:0xf bank_mask:0xf
	v_mov_b32_dpp v62, v26 row_shl:1 row_mask:0xf bank_mask:0xf
	v_mov_b32_dpp v63, v27 row_shl:1 row_mask:0xf bank_mask:0xf
	v_mov_b32_dpp v124, v28 row_shl:1 row_mask:0xf bank_mask:0xf
	v_mov_b32_dpp v125, v29 row_shl:1 row_mask:0xf bank_mask:0xf
	v_mov_b32_dpp v126, v30 row_shl:1 row_mask:0xf bank_mask:0xf
	v_mov_b32_dpp v127, v31 row_shl:1 row_mask:0xf bank_mask:0xf
	v_pk_fma_f32 v[12:13], v[4:5], v[12:13], v[112:113]
	v_pk_fma_f32 v[14:15], v[6:7], v[14:15], v[114:115]
	v_pk_fma_f32 v[40:41], v[32:33], v[40:41], v[152:153]
	v_pk_fma_f32 v[42:43], v[34:35], v[42:43], v[154:155]
	v_pk_fma_f32 v[12:13], v[24:25], v[68:69], v[12:13]
	v_pk_fma_f32 v[14:15], v[26:27], v[70:71], v[14:15]
	v_pk_fma_f32 v[40:41], v[28:29], v[80:81], v[40:41]
	v_pk_fma_f32 v[42:43], v[30:31], v[82:83], v[42:43]
	v_pk_fma_f32 v[12:13], v[92:93], v[120:121], v[12:13]
	v_pk_fma_f32 v[14:15], v[94:95], v[122:123], v[14:15]
	v_pk_fma_f32 v[40:41], v[100:101], v[108:109], v[40:41]
	v_pk_fma_f32 v[42:43], v[102:103], v[110:111], v[42:43]
	v_and_b32_e32 v212, 0x7fffffff, v12
	v_and_b32_e32 v213, 0x7fffffff, v13
	v_and_b32_e32 v158, 0x7fffffff, v14
	v_and_b32_e32 v159, 0x7fffffff, v15
	v_pk_fma_f32 v[238:239], v[212:213], s[90:91], 1.0 op_sel_hi:[1,0,0]
	v_pk_fma_f32 v[164:165], v[158:159], s[90:91], 1.0 op_sel_hi:[1,0,0]
	v_pk_mul_f32 v[156:157], v[12:13], v[12:13]
	v_pk_mul_f32 v[168:169], v[14:15], v[14:15]
	v_rcp_f32_e32 v238, v238
	v_rcp_f32_e32 v239, v239
	v_rcp_f32_e32 v164, v164
	v_rcp_f32_e32 v165, v165
	v_pk_mul_f32 v[156:157], v[156:157], s[44:45] op_sel_hi:[1,0]
	v_pk_mul_f32 v[168:169], v[168:169], s[44:45] op_sel_hi:[1,0]
	v_pk_fma_f32 v[246:247], v[238:239], s[92:93], v[236:237] op_sel_hi:[1,0,0]
	v_pk_fma_f32 v[166:167], v[164:165], s[92:93], v[236:237] op_sel_hi:[1,0,0]
	v_exp_f32_e32 v156, v156
	v_exp_f32_e32 v157, v157
	v_exp_f32_e32 v168, v168
	v_exp_f32_e32 v169, v169
	v_pk_fma_f32 v[246:247], v[238:239], v[246:247], s[96:97] op_sel_hi:[1,1,0]
	v_pk_fma_f32 v[166:167], v[164:165], v[166:167], s[96:97] op_sel_hi:[1,1,0]
	v_pk_fma_f32 v[246:247], v[238:239], v[246:247], s[0:1] op_sel_hi:[1,1,0]
	v_pk_fma_f32 v[166:167], v[164:165], v[166:167], s[0:1] op_sel_hi:[1,1,0]
	v_pk_fma_f32 v[246:247], v[238:239], v[246:247], s[4:5] op_sel_hi:[1,1,0]
	v_pk_fma_f32 v[166:167], v[164:165], v[166:167], s[4:5] op_sel_hi:[1,1,0]
	v_pk_mul_f32 v[246:247], v[238:239], v[246:247]
	v_pk_mul_f32 v[166:167], v[164:165], v[166:167]
	v_max_f32_e32 v238, 0, v12
	v_max_f32_e32 v239, 0, v13
	v_max_f32_e32 v164, 0, v14
	v_max_f32_e32 v165, 0, v15
	v_pk_mul_f32 v[246:247], v[156:157], v[246:247]
	v_pk_mul_f32 v[166:167], v[168:169], v[166:167]
	v_pk_fma_f32 v[156:157], v[212:213], v[246:247], v[238:239] neg_lo:[1,0,0] neg_hi:[1,0,0]
	v_pk_fma_f32 v[168:169], v[158:159], v[166:167], v[164:165] neg_lo:[1,0,0] neg_hi:[1,0,0]
	v_pk_mul_f32 v[246:247], v[156:157], v[40:41]
	v_pk_mul_f32 v[166:167], v[168:169], v[42:43]
	v_cvt_pk_bf16_f32 v162, v246, v247
	v_cvt_pk_bf16_f32 v163, v166, v167
	v_add_u32_e32 v235, -1, v227
	v_mov_b32_e32 v245, v228
	v_cmp_gt_u32_e64 s[38:39], s64, v235
	v_cmp_gt_u32_e32 vcc, s88, v245
	v_mov_b32_e32 v235, v230
	s_and_b64 s[38:39], s[38:39], vcc
	s_and_saveexec_b64 s[30:31], s[38:39]
	global_store_dwordx4 v235, v[160:163], s[50:51]
	s_mov_b64 exec, s[30:31]
	s_nop 1
	v_pk_fma_f32 v[24:25], v[4:5], v[24:25], v[112:113]
	v_pk_fma_f32 v[26:27], v[6:7], v[26:27], v[114:115]
	v_pk_fma_f32 v[28:29], v[32:33], v[28:29], v[152:153]
	v_pk_fma_f32 v[30:31], v[34:35], v[30:31], v[154:155]
	v_pk_fma_f32 v[24:25], v[120:121], v[68:69], v[24:25]
	v_pk_fma_f32 v[26:27], v[122:123], v[70:71], v[26:27]
	v_pk_fma_f32 v[28:29], v[108:109], v[80:81], v[28:29]
	v_pk_fma_f32 v[30:31], v[110:111], v[82:83], v[30:31]
	v_pk_fma_f32 v[24:25], v[92:93], v[104:105], v[24:25]
	v_pk_fma_f32 v[26:27], v[94:95], v[106:107], v[26:27]
	v_pk_fma_f32 v[28:29], v[100:101], v[96:97], v[28:29]
	v_pk_fma_f32 v[30:31], v[102:103], v[98:99], v[30:31]
	v_and_b32_e32 v212, 0x7fffffff, v24
	v_and_b32_e32 v213, 0x7fffffff, v25
	v_and_b32_e32 v14, 0x7fffffff, v26
	v_and_b32_e32 v15, 0x7fffffff, v27
	v_pk_fma_f32 v[238:239], v[212:213], s[90:91], 1.0 op_sel_hi:[1,0,0]
	v_pk_fma_f32 v[40:41], v[14:15], s[90:91], 1.0 op_sel_hi:[1,0,0]
	v_pk_mul_f32 v[12:13], v[24:25], v[24:25]
	v_pk_mul_f32 v[156:157], v[26:27], v[26:27]
	v_rcp_f32_e32 v238, v238
	v_rcp_f32_e32 v239, v239
	v_rcp_f32_e32 v40, v40
	v_rcp_f32_e32 v41, v41
	v_pk_mul_f32 v[12:13], v[12:13], s[44:45] op_sel_hi:[1,0]
	v_pk_mul_f32 v[156:157], v[156:157], s[44:45] op_sel_hi:[1,0]
	v_pk_fma_f32 v[246:247], v[238:239], s[92:93], v[236:237] op_sel_hi:[1,0,0]
	v_pk_fma_f32 v[42:43], v[40:41], s[92:93], v[236:237] op_sel_hi:[1,0,0]
	v_exp_f32_e32 v12, v12
	v_exp_f32_e32 v13, v13
	v_exp_f32_e32 v156, v156
	v_exp_f32_e32 v157, v157
	v_pk_fma_f32 v[246:247], v[238:239], v[246:247], s[96:97] op_sel_hi:[1,1,0]
	v_pk_fma_f32 v[42:43], v[40:41], v[42:43], s[96:97] op_sel_hi:[1,1,0]
	v_pk_fma_f32 v[246:247], v[238:239], v[246:247], s[0:1] op_sel_hi:[1,1,0]
	v_pk_fma_f32 v[42:43], v[40:41], v[42:43], s[0:1] op_sel_hi:[1,1,0]
	v_pk_fma_f32 v[246:247], v[238:239], v[246:247], s[4:5] op_sel_hi:[1,1,0]
	v_pk_fma_f32 v[42:43], v[40:41], v[42:43], s[4:5] op_sel_hi:[1,1,0]
	v_pk_mul_f32 v[246:247], v[238:239], v[246:247]
	v_pk_mul_f32 v[42:43], v[40:41], v[42:43]
	v_max_f32_e32 v238, 0, v24
	v_max_f32_e32 v239, 0, v25
	v_max_f32_e32 v40, 0, v26
	v_max_f32_e32 v41, 0, v27
	v_pk_mul_f32 v[246:247], v[12:13], v[246:247]
	v_pk_mul_f32 v[42:43], v[156:157], v[42:43]
	v_pk_fma_f32 v[12:13], v[212:213], v[246:247], v[238:239] neg_lo:[1,0,0] neg_hi:[1,0,0]
	v_pk_fma_f32 v[156:157], v[14:15], v[42:43], v[40:41] neg_lo:[1,0,0] neg_hi:[1,0,0]
	v_pk_mul_f32 v[246:247], v[12:13], v[28:29]
	v_pk_mul_f32 v[42:43], v[156:157], v[30:31]
	v_cvt_pk_bf16_f32 v58, v246, v247
	v_cvt_pk_bf16_f32 v59, v42, v43
	v_add_u32_e32 v235, 0, v227
	v_add_u32_e32 v245, 1, v228
	v_cmp_gt_u32_e64 s[38:39], s64, v235
	v_cmp_gt_u32_e32 vcc, s88, v245
	v_add_u32_e32 v235, 5632, v230
	s_and_b64 s[38:39], s[38:39], vcc
	s_and_saveexec_b64 s[30:31], s[38:39]
	global_store_dwordx4 v235, v[56:59], s[50:51]
	s_mov_b64 exec, s[30:31]
	s_nop 1
	v_pk_fma_f32 v[120:121], v[4:5], v[120:121], v[112:113]
	v_pk_fma_f32 v[122:123], v[6:7], v[122:123], v[114:115]
	v_pk_fma_f32 v[108:109], v[32:33], v[108:109], v[152:153]
	v_pk_fma_f32 v[110:111], v[34:35], v[110:111], v[154:155]
	v_pk_fma_f32 v[120:121], v[104:105], v[68:69], v[120:121]
	v_pk_fma_f32 v[122:123], v[106:107], v[70:71], v[122:123]
	v_pk_fma_f32 v[108:109], v[96:97], v[80:81], v[108:109]
	v_pk_fma_f32 v[110:111], v[98:99], v[82:83], v[110:111]
	v_pk_fma_f32 v[120:121], v[92:93], v[16:17], v[120:121]
	v_pk_fma_f32 v[122:123], v[94:95], v[18:19], v[122:123]
	v_pk_fma_f32 v[108:109], v[100:101], v[20:21], v[108:109]
	v_pk_fma_f32 v[110:111], v[102:103], v[22:23], v[110:111]
	ds_read_b128 v[12:15], v232 offset:16
	ds_read_b128 v[24:27], v232 offset:528
	ds_read_b128 v[28:31], v234 offset:16
	ds_read_b128 v[40:43], v234 offset:528
	v_and_b32_e32 v212, 0x7fffffff, v120
	v_and_b32_e32 v213, 0x7fffffff, v121
	v_and_b32_e32 v58, 0x7fffffff, v122
	v_and_b32_e32 v59, 0x7fffffff, v123
	v_pk_fma_f32 v[238:239], v[212:213], s[90:91], 1.0 op_sel_hi:[1,0,0]
	v_pk_fma_f32 v[156:157], v[58:59], s[90:91], 1.0 op_sel_hi:[1,0,0]
	v_pk_mul_f32 v[56:57], v[120:121], v[120:121]
	v_pk_mul_f32 v[160:161], v[122:123], v[122:123]
	v_rcp_f32_e32 v238, v238
	v_rcp_f32_e32 v239, v239
	v_rcp_f32_e32 v156, v156
	v_rcp_f32_e32 v157, v157
	v_pk_mul_f32 v[56:57], v[56:57], s[44:45] op_sel_hi:[1,0]
	v_pk_mul_f32 v[160:161], v[160:161], s[44:45] op_sel_hi:[1,0]
	v_pk_fma_f32 v[246:247], v[238:239], s[92:93], v[236:237] op_sel_hi:[1,0,0]
	v_pk_fma_f32 v[158:159], v[156:157], s[92:93], v[236:237] op_sel_hi:[1,0,0]
	v_exp_f32_e32 v56, v56
	v_exp_f32_e32 v57, v57
	v_exp_f32_e32 v160, v160
	v_exp_f32_e32 v161, v161
	v_pk_fma_f32 v[246:247], v[238:239], v[246:247], s[96:97] op_sel_hi:[1,1,0]
	v_pk_fma_f32 v[158:159], v[156:157], v[158:159], s[96:97] op_sel_hi:[1,1,0]
	v_pk_fma_f32 v[246:247], v[238:239], v[246:247], s[0:1] op_sel_hi:[1,1,0]
	v_pk_fma_f32 v[158:159], v[156:157], v[158:159], s[0:1] op_sel_hi:[1,1,0]
	v_pk_fma_f32 v[246:247], v[238:239], v[246:247], s[4:5] op_sel_hi:[1,1,0]
	v_pk_fma_f32 v[158:159], v[156:157], v[158:159], s[4:5] op_sel_hi:[1,1,0]
	v_pk_mul_f32 v[246:247], v[238:239], v[246:247]
	v_pk_mul_f32 v[158:159], v[156:157], v[158:159]
	v_max_f32_e32 v238, 0, v120
	v_max_f32_e32 v239, 0, v121
	v_max_f32_e32 v156, 0, v122
	v_max_f32_e32 v157, 0, v123
	v_pk_mul_f32 v[246:247], v[56:57], v[246:247]
	v_pk_mul_f32 v[158:159], v[160:161], v[158:159]
	v_pk_fma_f32 v[56:57], v[212:213], v[246:247], v[238:239] neg_lo:[1,0,0] neg_hi:[1,0,0]
	v_pk_fma_f32 v[160:161], v[58:59], v[158:159], v[156:157] neg_lo:[1,0,0] neg_hi:[1,0,0]
	v_pk_mul_f32 v[246:247], v[56:57], v[108:109]
	v_pk_mul_f32 v[158:159], v[160:161], v[110:111]
	v_cvt_pk_bf16_f32 v50, v246, v247
	v_cvt_pk_bf16_f32 v51, v158, v159
	v_add_u32_e32 v235, 1, v227
	v_add_u32_e32 v245, 2, v228
	v_cmp_gt_u32_e64 s[38:39], s64, v235
	v_cmp_gt_u32_e32 vcc, s88, v245
	v_add_u32_e32 v235, 11264, v230
	s_and_b64 s[38:39], s[38:39], vcc
	s_and_saveexec_b64 s[30:31], s[38:39]
	global_store_dwordx4 v235, v[48:51], s[50:51]
	s_mov_b64 exec, s[30:31]
	s_nop 1
	v_pk_fma_f32 v[104:105], v[4:5], v[104:105], v[112:113]
	v_pk_fma_f32 v[106:107], v[6:7], v[106:107], v[114:115]
	v_pk_fma_f32 v[96:97], v[32:33], v[96:97], v[152:153]
	v_pk_fma_f32 v[98:99], v[34:35], v[98:99], v[154:155]
	v_pk_fma_f32 v[104:105], v[16:17], v[68:69], v[104:105]
	v_pk_fma_f32 v[106:107], v[18:19], v[70:71], v[106:107]
	v_pk_fma_f32 v[96:97], v[20:21], v[80:81], v[96:97]
	v_pk_fma_f32 v[98:99], v[22:23], v[82:83], v[98:99]
	v_pk_fma_f32 v[104:105], v[92:93], v[60:61], v[104:105]
	v_pk_fma_f32 v[106:107], v[94:95], v[62:63], v[106:107]
	v_pk_fma_f32 v[96:97], v[100:101], v[124:125], v[96:97]
	v_pk_fma_f32 v[98:99], v[102:103], v[126:127], v[98:99]
	v_and_b32_e32 v212, 0x7fffffff, v104
	v_and_b32_e32 v213, 0x7fffffff, v105
	v_and_b32_e32 v50, 0x7fffffff, v106
	v_and_b32_e32 v51, 0x7fffffff, v107
	v_pk_fma_f32 v[238:239], v[212:213], s[90:91], 1.0 op_sel_hi:[1,0,0]
	v_pk_fma_f32 v[56:57], v[50:51], s[90:91], 1.0 op_sel_hi:[1,0,0]
	v_pk_mul_f32 v[48:49], v[104:105], v[104:105]
	v_pk_mul_f32 v[108:109], v[106:107], v[106:107]
	v_rcp_f32_e32 v238, v238
	v_rcp_f32_e32 v239, v239
	v_rcp_f32_e32 v56, v56
	v_rcp_f32_e32 v57, v57
	v_pk_mul_f32 v[48:49], v[48:49], s[44:45] op_sel_hi:[1,0]
	v_pk_mul_f32 v[108:109], v[108:109], s[44:45] op_sel_hi:[1,0]
	v_pk_fma_f32 v[246:247], v[238:239], s[92:93], v[236:237] op_sel_hi:[1,0,0]
	v_pk_fma_f32 v[58:59], v[56:57], s[92:93], v[236:237] op_sel_hi:[1,0,0]
	v_exp_f32_e32 v48, v48
	v_exp_f32_e32 v49, v49
	v_exp_f32_e32 v108, v108
	v_exp_f32_e32 v109, v109
	v_pk_fma_f32 v[246:247], v[238:239], v[246:247], s[96:97] op_sel_hi:[1,1,0]
	v_pk_fma_f32 v[58:59], v[56:57], v[58:59], s[96:97] op_sel_hi:[1,1,0]
	v_pk_fma_f32 v[246:247], v[238:239], v[246:247], s[0:1] op_sel_hi:[1,1,0]
	v_pk_fma_f32 v[58:59], v[56:57], v[58:59], s[0:1] op_sel_hi:[1,1,0]
	v_pk_fma_f32 v[246:247], v[238:239], v[246:247], s[4:5] op_sel_hi:[1,1,0]
	v_pk_fma_f32 v[58:59], v[56:57], v[58:59], s[4:5] op_sel_hi:[1,1,0]
	v_pk_mul_f32 v[246:247], v[238:239], v[246:247]
	v_pk_mul_f32 v[58:59], v[56:57], v[58:59]
	v_max_f32_e32 v238, 0, v104
	v_max_f32_e32 v239, 0, v105
	v_max_f32_e32 v56, 0, v106
	v_max_f32_e32 v57, 0, v107
	v_pk_mul_f32 v[246:247], v[48:49], v[246:247]
	v_pk_mul_f32 v[58:59], v[108:109], v[58:59]
	v_pk_fma_f32 v[48:49], v[212:213], v[246:247], v[238:239] neg_lo:[1,0,0] neg_hi:[1,0,0]
	v_pk_fma_f32 v[108:109], v[50:51], v[58:59], v[56:57] neg_lo:[1,0,0] neg_hi:[1,0,0]
	v_pk_mul_f32 v[246:247], v[48:49], v[96:97]
	v_pk_mul_f32 v[58:59], v[108:109], v[98:99]
	v_cvt_pk_bf16_f32 v54, v246, v247
	v_cvt_pk_bf16_f32 v55, v58, v59
	v_add_u32_e32 v235, 2, v227
	v_add_u32_e32 v245, 3, v228
	v_cmp_gt_u32_e64 s[38:39], s64, v235
	v_cmp_gt_u32_e32 vcc, s88, v245
	v_add_u32_e32 v235, 16896, v230
	s_and_b64 s[38:39], s[38:39], vcc
	s_and_saveexec_b64 s[30:31], s[38:39]
	global_store_dwordx4 v235, v[52:55], s[50:51]
	s_mov_b64 exec, s[30:31]
	s_nop 1
	s_waitcnt lgkmcnt(0)
	v_mov_b32_dpp v12, v0 row_shr:1 row_mask:0xf bank_mask:0xf
	v_mov_b32_dpp v13, v1 row_shr:1 row_mask:0xf bank_mask:0xf
	v_mov_b32_dpp v14, v2 row_shr:1 row_mask:0xf bank_mask:0xf
	v_mov_b32_dpp v15, v3 row_shr:1 row_mask:0xf bank_mask:0xf
	v_mov_b32_dpp v24, v128 row_shr:1 row_mask:0xf bank_mask:0xf
	v_mov_b32_dpp v25, v129 row_shr:1 row_mask:0xf bank_mask:0xf
	v_mov_b32_dpp v26, v130 row_shr:1 row_mask:0xf bank_mask:0xf
	v_mov_b32_dpp v27, v131 row_shr:1 row_mask:0xf bank_mask:0xf
	v_mov_b32_dpp v28, v8 row_shl:1 row_mask:0xf bank_mask:0xf
	v_mov_b32_dpp v29, v9 row_shl:1 row_mask:0xf bank_mask:0xf
	v_mov_b32_dpp v30, v10 row_shl:1 row_mask:0xf bank_mask:0xf
	v_mov_b32_dpp v31, v11 row_shl:1 row_mask:0xf bank_mask:0xf
	v_mov_b32_dpp v40, v36 row_shl:1 row_mask:0xf bank_mask:0xf
	v_mov_b32_dpp v41, v37 row_shl:1 row_mask:0xf bank_mask:0xf
	v_mov_b32_dpp v42, v38 row_shl:1 row_mask:0xf bank_mask:0xf
	v_mov_b32_dpp v43, v39 row_shl:1 row_mask:0xf bank_mask:0xf
	v_pk_fma_f32 v[12:13], v[4:5], v[12:13], v[112:113]
	v_pk_fma_f32 v[14:15], v[6:7], v[14:15], v[114:115]
	v_pk_fma_f32 v[24:25], v[32:33], v[24:25], v[152:153]
	v_pk_fma_f32 v[26:27], v[34:35], v[26:27], v[154:155]
	v_pk_fma_f32 v[12:13], v[8:9], v[68:69], v[12:13]
	v_pk_fma_f32 v[14:15], v[10:11], v[70:71], v[14:15]
	v_pk_fma_f32 v[24:25], v[36:37], v[80:81], v[24:25]
	v_pk_fma_f32 v[26:27], v[38:39], v[82:83], v[26:27]
	v_pk_fma_f32 v[12:13], v[92:93], v[88:89], v[12:13]
	v_pk_fma_f32 v[14:15], v[94:95], v[90:91], v[14:15]
	v_pk_fma_f32 v[24:25], v[100:101], v[76:77], v[24:25]
	v_pk_fma_f32 v[26:27], v[102:103], v[78:79], v[26:27]
	v_and_b32_e32 v212, 0x7fffffff, v12
	v_and_b32_e32 v213, 0x7fffffff, v13
	v_and_b32_e32 v18, 0x7fffffff, v14
	v_and_b32_e32 v19, 0x7fffffff, v15
	v_pk_fma_f32 v[238:239], v[212:213], s[90:91], 1.0 op_sel_hi:[1,0,0]
	v_pk_fma_f32 v[20:21], v[18:19], s[90:91], 1.0 op_sel_hi:[1,0,0]
	v_pk_mul_f32 v[16:17], v[12:13], v[12:13]
	v_pk_mul_f32 v[48:49], v[14:15], v[14:15]
	v_rcp_f32_e32 v238, v238
	v_rcp_f32_e32 v239, v239
	v_rcp_f32_e32 v20, v20
	v_rcp_f32_e32 v21, v21
	v_pk_mul_f32 v[16:17], v[16:17], s[44:45] op_sel_hi:[1,0]
	v_pk_mul_f32 v[48:49], v[48:49], s[44:45] op_sel_hi:[1,0]
	v_pk_fma_f32 v[246:247], v[238:239], s[92:93], v[236:237] op_sel_hi:[1,0,0]
	v_pk_fma_f32 v[22:23], v[20:21], s[92:93], v[236:237] op_sel_hi:[1,0,0]
	v_exp_f32_e32 v16, v16
	v_exp_f32_e32 v17, v17
	v_exp_f32_e32 v48, v48
	v_exp_f32_e32 v49, v49
	v_pk_fma_f32 v[246:247], v[238:239], v[246:247], s[96:97] op_sel_hi:[1,1,0]
	v_pk_fma_f32 v[22:23], v[20:21], v[22:23], s[96:97] op_sel_hi:[1,1,0]
	v_pk_fma_f32 v[246:247], v[238:239], v[246:247], s[0:1] op_sel_hi:[1,1,0]
	v_pk_fma_f32 v[22:23], v[20:21], v[22:23], s[0:1] op_sel_hi:[1,1,0]
	v_pk_fma_f32 v[246:247], v[238:239], v[246:247], s[4:5] op_sel_hi:[1,1,0]
	v_pk_fma_f32 v[22:23], v[20:21], v[22:23], s[4:5] op_sel_hi:[1,1,0]
	v_pk_mul_f32 v[246:247], v[238:239], v[246:247]
	v_pk_mul_f32 v[22:23], v[20:21], v[22:23]
	v_max_f32_e32 v238, 0, v12
	v_max_f32_e32 v239, 0, v13
	v_max_f32_e32 v20, 0, v14
	v_max_f32_e32 v21, 0, v15
	v_pk_mul_f32 v[246:247], v[16:17], v[246:247]
	v_pk_mul_f32 v[22:23], v[48:49], v[22:23]
	v_pk_fma_f32 v[16:17], v[212:213], v[246:247], v[238:239] neg_lo:[1,0,0] neg_hi:[1,0,0]
	v_pk_fma_f32 v[48:49], v[18:19], v[22:23], v[20:21] neg_lo:[1,0,0] neg_hi:[1,0,0]
	v_pk_mul_f32 v[246:247], v[16:17], v[24:25]
	v_pk_mul_f32 v[22:23], v[48:49], v[26:27]
	v_cvt_pk_bf16_f32 v118, v246, v247
	v_cvt_pk_bf16_f32 v119, v22, v23
	v_add_u32_e32 v235, 127, v227
	v_add_u32_e32 v245, 128, v228
	v_cmp_gt_u32_e64 s[38:39], s64, v235
	v_cmp_gt_u32_e32 vcc, s88, v245
	v_add_u32_e32 v235, 720896, v230
	s_and_b64 s[38:39], s[38:39], vcc
	s_and_saveexec_b64 s[30:31], s[38:39]
	global_store_dwordx4 v235, v[116:119], s[50:51]
	s_mov_b64 exec, s[30:31]
	s_nop 1
	v_pk_fma_f32 v[8:9], v[4:5], v[8:9], v[112:113]
	v_pk_fma_f32 v[10:11], v[6:7], v[10:11], v[114:115]
	v_pk_fma_f32 v[36:37], v[32:33], v[36:37], v[152:153]
	v_pk_fma_f32 v[38:39], v[34:35], v[38:39], v[154:155]
	v_pk_fma_f32 v[8:9], v[88:89], v[68:69], v[8:9]
	v_pk_fma_f32 v[10:11], v[90:91], v[70:71], v[10:11]
	v_pk_fma_f32 v[36:37], v[76:77], v[80:81], v[36:37]
	v_pk_fma_f32 v[38:39], v[78:79], v[82:83], v[38:39]
	v_pk_fma_f32 v[8:9], v[92:93], v[72:73], v[8:9]
	v_pk_fma_f32 v[10:11], v[94:95], v[74:75], v[10:11]
	v_pk_fma_f32 v[36:37], v[100:101], v[64:65], v[36:37]
	v_pk_fma_f32 v[38:39], v[102:103], v[66:67], v[38:39]
	v_and_b32_e32 v212, 0x7fffffff, v8
	v_and_b32_e32 v213, 0x7fffffff, v9
	v_and_b32_e32 v14, 0x7fffffff, v10
	v_and_b32_e32 v15, 0x7fffffff, v11
	v_pk_fma_f32 v[238:239], v[212:213], s[90:91], 1.0 op_sel_hi:[1,0,0]
	v_pk_fma_f32 v[16:17], v[14:15], s[90:91], 1.0 op_sel_hi:[1,0,0]
	v_pk_mul_f32 v[12:13], v[8:9], v[8:9]
	v_pk_mul_f32 v[20:21], v[10:11], v[10:11]
	v_rcp_f32_e32 v238, v238
	v_rcp_f32_e32 v239, v239
	v_rcp_f32_e32 v16, v16
	v_rcp_f32_e32 v17, v17
	v_pk_mul_f32 v[12:13], v[12:13], s[44:45] op_sel_hi:[1,0]
	v_pk_mul_f32 v[20:21], v[20:21], s[44:45] op_sel_hi:[1,0]
	v_pk_fma_f32 v[246:247], v[238:239], s[92:93], v[236:237] op_sel_hi:[1,0,0]
	v_pk_fma_f32 v[18:19], v[16:17], s[92:93], v[236:237] op_sel_hi:[1,0,0]
	v_exp_f32_e32 v12, v12
	v_exp_f32_e32 v13, v13
	v_exp_f32_e32 v20, v20
	v_exp_f32_e32 v21, v21
	v_pk_fma_f32 v[246:247], v[238:239], v[246:247], s[96:97] op_sel_hi:[1,1,0]
	v_pk_fma_f32 v[18:19], v[16:17], v[18:19], s[96:97] op_sel_hi:[1,1,0]
	v_pk_fma_f32 v[246:247], v[238:239], v[246:247], s[0:1] op_sel_hi:[1,1,0]
	v_pk_fma_f32 v[18:19], v[16:17], v[18:19], s[0:1] op_sel_hi:[1,1,0]
	v_pk_fma_f32 v[246:247], v[238:239], v[246:247], s[4:5] op_sel_hi:[1,1,0]
	v_pk_fma_f32 v[18:19], v[16:17], v[18:19], s[4:5] op_sel_hi:[1,1,0]
	v_pk_mul_f32 v[246:247], v[238:239], v[246:247]
	v_pk_mul_f32 v[18:19], v[16:17], v[18:19]
	v_max_f32_e32 v238, 0, v8
	v_max_f32_e32 v239, 0, v9
	v_max_f32_e32 v16, 0, v10
	v_max_f32_e32 v17, 0, v11
	v_pk_mul_f32 v[246:247], v[12:13], v[246:247]
	v_pk_mul_f32 v[18:19], v[20:21], v[18:19]
	v_pk_fma_f32 v[12:13], v[212:213], v[246:247], v[238:239] neg_lo:[1,0,0] neg_hi:[1,0,0]
	v_pk_fma_f32 v[20:21], v[14:15], v[18:19], v[16:17] neg_lo:[1,0,0] neg_hi:[1,0,0]
	v_pk_mul_f32 v[246:247], v[12:13], v[36:37]
	v_pk_mul_f32 v[18:19], v[20:21], v[38:39]
	v_cvt_pk_bf16_f32 v46, v246, v247
	v_cvt_pk_bf16_f32 v47, v18, v19
	v_add_u32_e32 v235, 128, v227
	v_add_u32_e32 v245, 129, v228
	v_cmp_gt_u32_e64 s[38:39], s64, v235
	v_cmp_gt_u32_e32 vcc, s88, v245
	v_add_u32_e32 v235, 726528, v230
	s_and_b64 s[38:39], s[38:39], vcc
	s_and_saveexec_b64 s[30:31], s[38:39]
	global_store_dwordx4 v235, v[44:47], s[50:51]
	s_mov_b64 exec, s[30:31]
	s_nop 1
	v_pk_fma_f32 v[88:89], v[4:5], v[88:89], v[112:113]
	v_pk_fma_f32 v[90:91], v[6:7], v[90:91], v[114:115]
	v_pk_fma_f32 v[76:77], v[32:33], v[76:77], v[152:153]
	v_pk_fma_f32 v[78:79], v[34:35], v[78:79], v[154:155]
	v_pk_fma_f32 v[88:89], v[72:73], v[68:69], v[88:89]
	v_pk_fma_f32 v[90:91], v[74:75], v[70:71], v[90:91]
	v_pk_fma_f32 v[76:77], v[64:65], v[80:81], v[76:77]
	v_pk_fma_f32 v[78:79], v[66:67], v[82:83], v[78:79]
	v_pk_fma_f32 v[88:89], v[92:93], v[0:1], v[88:89]
	v_pk_fma_f32 v[90:91], v[94:95], v[2:3], v[90:91]
	v_pk_fma_f32 v[76:77], v[100:101], v[128:129], v[76:77]
	v_pk_fma_f32 v[78:79], v[102:103], v[130:131], v[78:79]
	v_and_b32_e32 v212, 0x7fffffff, v88
	v_and_b32_e32 v213, 0x7fffffff, v89
	v_and_b32_e32 v10, 0x7fffffff, v90
	v_and_b32_e32 v11, 0x7fffffff, v91
	v_pk_fma_f32 v[238:239], v[212:213], s[90:91], 1.0 op_sel_hi:[1,0,0]
	v_pk_fma_f32 v[12:13], v[10:11], s[90:91], 1.0 op_sel_hi:[1,0,0]
	v_pk_mul_f32 v[8:9], v[88:89], v[88:89]
	v_pk_mul_f32 v[16:17], v[90:91], v[90:91]
	v_rcp_f32_e32 v238, v238
	v_rcp_f32_e32 v239, v239
	v_rcp_f32_e32 v12, v12
	v_rcp_f32_e32 v13, v13
	v_pk_mul_f32 v[8:9], v[8:9], s[44:45] op_sel_hi:[1,0]
	v_pk_mul_f32 v[16:17], v[16:17], s[44:45] op_sel_hi:[1,0]
	v_pk_fma_f32 v[246:247], v[238:239], s[92:93], v[236:237] op_sel_hi:[1,0,0]
	v_pk_fma_f32 v[14:15], v[12:13], s[92:93], v[236:237] op_sel_hi:[1,0,0]
	v_exp_f32_e32 v8, v8
	v_exp_f32_e32 v9, v9
	v_exp_f32_e32 v16, v16
	v_exp_f32_e32 v17, v17
	v_pk_fma_f32 v[246:247], v[238:239], v[246:247], s[96:97] op_sel_hi:[1,1,0]
	v_pk_fma_f32 v[14:15], v[12:13], v[14:15], s[96:97] op_sel_hi:[1,1,0]
	v_pk_fma_f32 v[246:247], v[238:239], v[246:247], s[0:1] op_sel_hi:[1,1,0]
	v_pk_fma_f32 v[14:15], v[12:13], v[14:15], s[0:1] op_sel_hi:[1,1,0]
	v_pk_fma_f32 v[246:247], v[238:239], v[246:247], s[4:5] op_sel_hi:[1,1,0]
	v_pk_fma_f32 v[14:15], v[12:13], v[14:15], s[4:5] op_sel_hi:[1,1,0]
	v_pk_mul_f32 v[246:247], v[238:239], v[246:247]
	v_pk_mul_f32 v[14:15], v[12:13], v[14:15]
	v_max_f32_e32 v238, 0, v88
	v_max_f32_e32 v239, 0, v89
	v_max_f32_e32 v12, 0, v90
	v_max_f32_e32 v13, 0, v91
	v_pk_mul_f32 v[246:247], v[8:9], v[246:247]
	v_pk_mul_f32 v[14:15], v[16:17], v[14:15]
	v_pk_fma_f32 v[8:9], v[212:213], v[246:247], v[238:239] neg_lo:[1,0,0] neg_hi:[1,0,0]
	v_pk_fma_f32 v[16:17], v[10:11], v[14:15], v[12:13] neg_lo:[1,0,0] neg_hi:[1,0,0]
	v_pk_mul_f32 v[246:247], v[8:9], v[76:77]
	v_pk_mul_f32 v[14:15], v[16:17], v[78:79]
	v_cvt_pk_bf16_f32 v134, v246, v247
	v_cvt_pk_bf16_f32 v135, v14, v15
	v_add_u32_e32 v235, 129, v227
	v_add_u32_e32 v245, 130, v228
	v_cmp_gt_u32_e64 s[38:39], s64, v235
	v_cmp_gt_u32_e32 vcc, s88, v245
	v_add_u32_e32 v235, 732160, v230
	s_and_b64 s[38:39], s[38:39], vcc
	s_and_saveexec_b64 s[30:31], s[38:39]
	global_store_dwordx4 v235, v[132:135], s[50:51]
	s_mov_b64 exec, s[30:31]
	s_nop 1
	v_pk_fma_f32 v[72:73], v[4:5], v[72:73], v[112:113]
	v_pk_fma_f32 v[74:75], v[6:7], v[74:75], v[114:115]
	v_pk_fma_f32 v[64:65], v[32:33], v[64:65], v[152:153]
	v_pk_fma_f32 v[66:67], v[34:35], v[66:67], v[154:155]
	v_pk_fma_f32 v[72:73], v[0:1], v[68:69], v[72:73]
	v_pk_fma_f32 v[74:75], v[2:3], v[70:71], v[74:75]
	v_pk_fma_f32 v[64:65], v[128:129], v[80:81], v[64:65]
	v_pk_fma_f32 v[66:67], v[130:131], v[82:83], v[66:67]
	v_pk_fma_f32 v[72:73], v[92:93], v[28:29], v[72:73]
	v_pk_fma_f32 v[74:75], v[94:95], v[30:31], v[74:75]
	v_pk_fma_f32 v[64:65], v[100:101], v[40:41], v[64:65]
	v_pk_fma_f32 v[66:67], v[102:103], v[42:43], v[66:67]
	v_and_b32_e32 v212, 0x7fffffff, v72
	v_and_b32_e32 v213, 0x7fffffff, v73
	v_and_b32_e32 v10, 0x7fffffff, v74
	v_and_b32_e32 v11, 0x7fffffff, v75
	v_pk_fma_f32 v[238:239], v[212:213], s[90:91], 1.0 op_sel_hi:[1,0,0]
	v_pk_fma_f32 v[12:13], v[10:11], s[90:91], 1.0 op_sel_hi:[1,0,0]
	v_pk_mul_f32 v[8:9], v[72:73], v[72:73]
	v_pk_mul_f32 v[16:17], v[74:75], v[74:75]
	v_rcp_f32_e32 v238, v238
	v_rcp_f32_e32 v239, v239
	v_rcp_f32_e32 v12, v12
	v_rcp_f32_e32 v13, v13
	v_pk_mul_f32 v[8:9], v[8:9], s[44:45] op_sel_hi:[1,0]
	v_pk_mul_f32 v[16:17], v[16:17], s[44:45] op_sel_hi:[1,0]
	v_pk_fma_f32 v[246:247], v[238:239], s[92:93], v[236:237] op_sel_hi:[1,0,0]
	v_pk_fma_f32 v[14:15], v[12:13], s[92:93], v[236:237] op_sel_hi:[1,0,0]
	v_exp_f32_e32 v8, v8
	v_exp_f32_e32 v9, v9
	v_exp_f32_e32 v16, v16
	v_exp_f32_e32 v17, v17
	v_pk_fma_f32 v[246:247], v[238:239], v[246:247], s[96:97] op_sel_hi:[1,1,0]
	v_pk_fma_f32 v[14:15], v[12:13], v[14:15], s[96:97] op_sel_hi:[1,1,0]
	v_pk_fma_f32 v[246:247], v[238:239], v[246:247], s[0:1] op_sel_hi:[1,1,0]
	v_pk_fma_f32 v[14:15], v[12:13], v[14:15], s[0:1] op_sel_hi:[1,1,0]
	v_pk_fma_f32 v[246:247], v[238:239], v[246:247], s[4:5] op_sel_hi:[1,1,0]
	v_pk_fma_f32 v[14:15], v[12:13], v[14:15], s[4:5] op_sel_hi:[1,1,0]
	v_pk_mul_f32 v[246:247], v[238:239], v[246:247]
	v_pk_mul_f32 v[14:15], v[12:13], v[14:15]
	v_max_f32_e32 v238, 0, v72
	v_max_f32_e32 v239, 0, v73
	v_max_f32_e32 v12, 0, v74
	v_max_f32_e32 v13, 0, v75
	v_pk_mul_f32 v[246:247], v[8:9], v[246:247]
	v_pk_mul_f32 v[14:15], v[16:17], v[14:15]
	v_pk_fma_f32 v[8:9], v[212:213], v[246:247], v[238:239] neg_lo:[1,0,0] neg_hi:[1,0,0]
	v_pk_fma_f32 v[16:17], v[10:11], v[14:15], v[12:13] neg_lo:[1,0,0] neg_hi:[1,0,0]
	v_pk_mul_f32 v[246:247], v[8:9], v[64:65]
	v_pk_mul_f32 v[14:15], v[16:17], v[66:67]
	v_cvt_pk_bf16_f32 v86, v246, v247
	v_cvt_pk_bf16_f32 v87, v14, v15
	v_add_u32_e32 v235, 130, v227
	v_add_u32_e32 v245, 131, v228
	v_cmp_gt_u32_e64 s[38:39], s64, v235
	v_cmp_gt_u32_e32 vcc, s88, v245
	v_add_u32_e32 v235, 737792, v230
	s_and_b64 s[38:39], s[38:39], vcc
	s_and_saveexec_b64 s[30:31], s[38:39]
	global_store_dwordx4 v235, v[84:87], s[50:51]
	s_mov_b64 exec, s[30:31]
	s_nop 1
	s_branch .Lp5_done
.Lp5_edge:
	ds_read_b128 v[56:59], v231 offset:0
	ds_read_b128 v[132:135], v231 offset:512
	ds_read_b128 v[152:155], v233 offset:0
	ds_read_b128 v[156:159], v233 offset:512
	s_waitcnt lgkmcnt(0)
	v_mov_b32_dpp v56, v60 row_shr:1 row_mask:0xf bank_mask:0xf
	v_mov_b32_dpp v57, v61 row_shr:1 row_mask:0xf bank_mask:0xf
	v_mov_b32_dpp v58, v62 row_shr:1 row_mask:0xf bank_mask:0xf
	v_mov_b32_dpp v59, v63 row_shr:1 row_mask:0xf bank_mask:0xf
	v_mov_b32_dpp v132, v44 row_shr:1 row_mask:0xf bank_mask:0xf
	v_mov_b32_dpp v133, v45 row_shr:1 row_mask:0xf bank_mask:0xf
	v_mov_b32_dpp v134, v46 row_shr:1 row_mask:0xf bank_mask:0xf
	v_mov_b32_dpp v135, v47 row_shr:1 row_mask:0xf bank_mask:0xf
	v_mov_b32_dpp v152, v48 row_shl:1 row_mask:0xf bank_mask:0xf
	v_mov_b32_dpp v153, v49 row_shl:1 row_mask:0xf bank_mask:0xf
	v_mov_b32_dpp v154, v50 row_shl:1 row_mask:0xf bank_mask:0xf
	v_mov_b32_dpp v155, v51 row_shl:1 row_mask:0xf bank_mask:0xf
	v_mov_b32_dpp v156, v52 row_shl:1 row_mask:0xf bank_mask:0xf
	v_mov_b32_dpp v157, v53 row_shl:1 row_mask:0xf bank_mask:0xf
	v_mov_b32_dpp v158, v54 row_shl:1 row_mask:0xf bank_mask:0xf
	v_mov_b32_dpp v159, v55 row_shl:1 row_mask:0xf bank_mask:0xf
	v_mov_b32_e32 v235, v228
	v_cmp_gt_i32_e32 vcc, 0x4000, v235
	s_nop 1
	v_cndmask_b32_e32 v245, v222, v221, vcc
	v_and_b32_e32 v235, v235, v245
	v_cmp_eq_u32_e64 s[34:35], 0, v235
	v_cmp_eq_u32_e64 s[36:37], v235, v245
	s_nop 1
	v_cndmask_b32_e64 v56, v56, 0, s[34:35]
	v_cndmask_b32_e64 v57, v57, 0, s[34:35]
	v_cndmask_b32_e64 v58, v58, 0, s[34:35]
	v_cndmask_b32_e64 v59, v59, 0, s[34:35]
	v_cndmask_b32_e64 v132, v132, 0, s[34:35]
	v_cndmask_b32_e64 v133, v133, 0, s[34:35]
	v_cndmask_b32_e64 v134, v134, 0, s[34:35]
	v_cndmask_b32_e64 v135, v135, 0, s[34:35]
	v_pk_fma_f32 v[56:57], v[176:177], v[56:57], v[200:201]
	v_pk_fma_f32 v[58:59], v[178:179], v[58:59], v[202:203]
	v_pk_fma_f32 v[132:133], v[180:181], v[132:133], v[204:205]
	v_pk_fma_f32 v[134:135], v[182:183], v[134:135], v[206:207]
	v_pk_fma_f32 v[56:57], v[48:49], v[184:185], v[56:57]
	v_pk_fma_f32 v[58:59], v[50:51], v[186:187], v[58:59]
	v_pk_fma_f32 v[132:133], v[52:53], v[188:189], v[132:133]
	v_pk_fma_f32 v[134:135], v[54:55], v[190:191], v[134:135]
	s_mov_b64 s[30:31], exec
	s_andn2_b64 exec, exec, s[36:37]
	v_pk_fma_f32 v[56:57], v[192:193], v[124:125], v[56:57]
	v_pk_fma_f32 v[58:59], v[194:195], v[126:127], v[58:59]
	v_pk_fma_f32 v[132:133], v[196:197], v[116:117], v[132:133]
	v_pk_fma_f32 v[134:135], v[198:199], v[118:119], v[134:135]
	s_mov_b64 exec, s[30:31]
	v_and_b32_e32 v212, 0x7fffffff, v56
	v_and_b32_e32 v213, 0x7fffffff, v57
	v_and_b32_e32 v166, 0x7fffffff, v58
	v_and_b32_e32 v167, 0x7fffffff, v59
	v_pk_fma_f32 v[238:239], v[212:213], s[90:91], 1.0 op_sel_hi:[1,0,0]
	v_pk_fma_f32 v[168:169], v[166:167], s[90:91], 1.0 op_sel_hi:[1,0,0]
	v_pk_mul_f32 v[164:165], v[56:57], v[56:57]
	v_pk_mul_f32 v[172:173], v[58:59], v[58:59]
	v_rcp_f32_e32 v238, v238
	v_rcp_f32_e32 v239, v239
	v_rcp_f32_e32 v168, v168
	v_rcp_f32_e32 v169, v169
	v_pk_mul_f32 v[164:165], v[164:165], s[44:45] op_sel_hi:[1,0]
	v_pk_mul_f32 v[172:173], v[172:173], s[44:45] op_sel_hi:[1,0]
	v_pk_fma_f32 v[246:247], v[238:239], s[92:93], v[236:237] op_sel_hi:[1,0,0]
	v_pk_fma_f32 v[170:171], v[168:169], s[92:93], v[236:237] op_sel_hi:[1,0,0]
	v_exp_f32_e32 v164, v164
	v_exp_f32_e32 v165, v165
	v_exp_f32_e32 v172, v172
	v_exp_f32_e32 v173, v173
	v_pk_fma_f32 v[246:247], v[238:239], v[246:247], s[96:97] op_sel_hi:[1,1,0]
	v_pk_fma_f32 v[170:171], v[168:169], v[170:171], s[96:97] op_sel_hi:[1,1,0]
	v_pk_fma_f32 v[246:247], v[238:239], v[246:247], s[0:1] op_sel_hi:[1,1,0]
	v_pk_fma_f32 v[170:171], v[168:169], v[170:171], s[0:1] op_sel_hi:[1,1,0]
	v_pk_fma_f32 v[246:247], v[238:239], v[246:247], s[4:5] op_sel_hi:[1,1,0]
	v_pk_fma_f32 v[170:171], v[168:169], v[170:171], s[4:5] op_sel_hi:[1,1,0]
	v_pk_mul_f32 v[246:247], v[238:239], v[246:247]
	v_pk_mul_f32 v[170:171], v[168:169], v[170:171]
	v_max_f32_e32 v238, 0, v56
	v_max_f32_e32 v239, 0, v57
	v_max_f32_e32 v168, 0, v58
	v_max_f32_e32 v169, 0, v59
	v_pk_mul_f32 v[246:247], v[164:165], v[246:247]
	v_pk_mul_f32 v[170:171], v[172:173], v[170:171]
	v_pk_fma_f32 v[164:165], v[212:213], v[246:247], v[238:239] neg_lo:[1,0,0] neg_hi:[1,0,0]
	v_pk_fma_f32 v[172:173], v[166:167], v[170:171], v[168:169] neg_lo:[1,0,0] neg_hi:[1,0,0]
	v_pk_mul_f32 v[246:247], v[164:165], v[132:133]
	v_pk_mul_f32 v[170:171], v[172:173], v[134:135]
	v_cvt_pk_bf16_f32 v160, v246, v247
	v_cvt_pk_bf16_f32 v161, v170, v171
	v_add_u32_e32 v235, 1, v228
	v_cmp_gt_i32_e32 vcc, 0x4000, v235
	s_nop 1
	v_cndmask_b32_e32 v245, v222, v221, vcc
	v_and_b32_e32 v235, v235, v245
	v_cmp_eq_u32_e64 s[34:35], 0, v235
	v_cmp_eq_u32_e64 s[36:37], v235, v245
	s_nop 1
	v_cndmask_b32_e64 v48, v48, 0, s[34:35]
	v_cndmask_b32_e64 v49, v49, 0, s[34:35]
	v_cndmask_b32_e64 v50, v50, 0, s[34:35]
	v_cndmask_b32_e64 v51, v51, 0, s[34:35]
	v_cndmask_b32_e64 v52, v52, 0, s[34:35]
	v_cndmask_b32_e64 v53, v53, 0, s[34:35]
	v_cndmask_b32_e64 v54, v54, 0, s[34:35]
	v_cndmask_b32_e64 v55, v55, 0, s[34:35]
	v_pk_fma_f32 v[48:49], v[176:177], v[48:49], v[200:201]
	v_pk_fma_f32 v[50:51], v[178:179], v[50:51], v[202:203]
	v_pk_fma_f32 v[52:53], v[180:181], v[52:53], v[204:205]
	v_pk_fma_f32 v[54:55], v[182:183], v[54:55], v[206:207]
	v_pk_fma_f32 v[48:49], v[124:125], v[184:185], v[48:49]
	v_pk_fma_f32 v[50:51], v[126:127], v[186:187], v[50:51]
	v_pk_fma_f32 v[52:53], v[116:117], v[188:189], v[52:53]
	v_pk_fma_f32 v[54:55], v[118:119], v[190:191], v[54:55]
	s_mov_b64 s[30:31], exec
	s_andn2_b64 exec, exec, s[36:37]
	v_pk_fma_f32 v[48:49], v[192:193], v[112:113], v[48:49]
	v_pk_fma_f32 v[50:51], v[194:195], v[114:115], v[50:51]
	v_pk_fma_f32 v[52:53], v[196:197], v[100:101], v[52:53]
	v_pk_fma_f32 v[54:55], v[198:199], v[102:103], v[54:55]
	s_mov_b64 exec, s[30:31]
	v_and_b32_e32 v212, 0x7fffffff, v48
	v_and_b32_e32 v213, 0x7fffffff, v49
	v_and_b32_e32 v134, 0x7fffffff, v50
	v_and_b32_e32 v135, 0x7fffffff, v51
	v_pk_fma_f32 v[238:239], v[212:213], s[90:91], 1.0 op_sel_hi:[1,0,0]
	v_pk_fma_f32 v[164:165], v[134:135], s[90:91], 1.0 op_sel_hi:[1,0,0]
	v_pk_mul_f32 v[132:133], v[48:49], v[48:49]
	v_pk_mul_f32 v[168:169], v[50:51], v[50:51]
	v_rcp_f32_e32 v238, v238
	v_rcp_f32_e32 v239, v239
	v_rcp_f32_e32 v164, v164
	v_rcp_f32_e32 v165, v165
	v_pk_mul_f32 v[132:133], v[132:133], s[44:45] op_sel_hi:[1,0]
	v_pk_mul_f32 v[168:169], v[168:169], s[44:45] op_sel_hi:[1,0]
	v_pk_fma_f32 v[246:247], v[238:239], s[92:93], v[236:237] op_sel_hi:[1,0,0]
	v_pk_fma_f32 v[166:167], v[164:165], s[92:93], v[236:237] op_sel_hi:[1,0,0]
	v_exp_f32_e32 v132, v132
	v_exp_f32_e32 v133, v133
	v_exp_f32_e32 v168, v168
	v_exp_f32_e32 v169, v169
	v_pk_fma_f32 v[246:247], v[238:239], v[246:247], s[96:97] op_sel_hi:[1,1,0]
	v_pk_fma_f32 v[166:167], v[164:165], v[166:167], s[96:97] op_sel_hi:[1,1,0]
	v_pk_fma_f32 v[246:247], v[238:239], v[246:247], s[0:1] op_sel_hi:[1,1,0]
	v_pk_fma_f32 v[166:167], v[164:165], v[166:167], s[0:1] op_sel_hi:[1,1,0]
	v_pk_fma_f32 v[246:247], v[238:239], v[246:247], s[4:5] op_sel_hi:[1,1,0]
	v_pk_fma_f32 v[166:167], v[164:165], v[166:167], s[4:5] op_sel_hi:[1,1,0]
	v_pk_mul_f32 v[246:247], v[238:239], v[246:247]
	v_pk_mul_f32 v[166:167], v[164:165], v[166:167]
	v_max_f32_e32 v238, 0, v48
	v_max_f32_e32 v239, 0, v49
	v_max_f32_e32 v164, 0, v50
	v_max_f32_e32 v165, 0, v51
	v_pk_mul_f32 v[246:247], v[132:133], v[246:247]
	v_pk_mul_f32 v[166:167], v[168:169], v[166:167]
	v_pk_fma_f32 v[132:133], v[212:213], v[246:247], v[238:239] neg_lo:[1,0,0] neg_hi:[1,0,0]
	v_pk_fma_f32 v[168:169], v[134:135], v[166:167], v[164:165] neg_lo:[1,0,0] neg_hi:[1,0,0]
	v_pk_mul_f32 v[246:247], v[132:133], v[52:53]
	v_pk_mul_f32 v[166:167], v[168:169], v[54:55]
	v_cvt_pk_bf16_f32 v56, v246, v247
	v_cvt_pk_bf16_f32 v57, v166, v167
	v_add_u32_e32 v235, 2, v228
	v_cmp_gt_i32_e32 vcc, 0x4000, v235
	s_nop 1
	v_cndmask_b32_e32 v245, v222, v221, vcc
	v_and_b32_e32 v235, v235, v245
	v_cmp_eq_u32_e64 s[34:35], 0, v235
	v_cmp_eq_u32_e64 s[36:37], v235, v245
	s_nop 1
	v_cndmask_b32_e64 v124, v124, 0, s[34:35]
	v_cndmask_b32_e64 v125, v125, 0, s[34:35]
	v_cndmask_b32_e64 v126, v126, 0, s[34:35]
	v_cndmask_b32_e64 v127, v127, 0, s[34:35]
	v_cndmask_b32_e64 v116, v116, 0, s[34:35]
	v_cndmask_b32_e64 v117, v117, 0, s[34:35]
	v_cndmask_b32_e64 v118, v118, 0, s[34:35]
	v_cndmask_b32_e64 v119, v119, 0, s[34:35]
	v_pk_fma_f32 v[124:125], v[176:177], v[124:125], v[200:201]
	v_pk_fma_f32 v[126:127], v[178:179], v[126:127], v[202:203]
	v_pk_fma_f32 v[116:117], v[180:181], v[116:117], v[204:205]
	v_pk_fma_f32 v[118:119], v[182:183], v[118:119], v[206:207]
	v_pk_fma_f32 v[124:125], v[112:113], v[184:185], v[124:125]
	v_pk_fma_f32 v[126:127], v[114:115], v[186:187], v[126:127]
	v_pk_fma_f32 v[116:117], v[100:101], v[188:189], v[116:117]
	v_pk_fma_f32 v[118:119], v[102:103], v[190:191], v[118:119]
	s_mov_b64 s[30:31], exec
	s_andn2_b64 exec, exec, s[36:37]
	v_pk_fma_f32 v[124:125], v[192:193], v[60:61], v[124:125]
	v_pk_fma_f32 v[126:127], v[194:195], v[62:63], v[126:127]
	v_pk_fma_f32 v[116:117], v[196:197], v[44:45], v[116:117]
	v_pk_fma_f32 v[118:119], v[198:199], v[46:47], v[118:119]
	s_mov_b64 exec, s[30:31]
	v_and_b32_e32 v212, 0x7fffffff, v124
	v_and_b32_e32 v213, 0x7fffffff, v125
	v_and_b32_e32 v54, 0x7fffffff, v126
	v_and_b32_e32 v55, 0x7fffffff, v127
	v_pk_fma_f32 v[238:239], v[212:213], s[90:91], 1.0 op_sel_hi:[1,0,0]
	v_pk_fma_f32 v[132:133], v[54:55], s[90:91], 1.0 op_sel_hi:[1,0,0]
	v_pk_mul_f32 v[52:53], v[124:125], v[124:125]
	v_pk_mul_f32 v[164:165], v[126:127], v[126:127]
	v_rcp_f32_e32 v238, v238
	v_rcp_f32_e32 v239, v239
	v_rcp_f32_e32 v132, v132
	v_rcp_f32_e32 v133, v133
	v_pk_mul_f32 v[52:53], v[52:53], s[44:45] op_sel_hi:[1,0]
	v_pk_mul_f32 v[164:165], v[164:165], s[44:45] op_sel_hi:[1,0]
	v_pk_fma_f32 v[246:247], v[238:239], s[92:93], v[236:237] op_sel_hi:[1,0,0]
	v_pk_fma_f32 v[134:135], v[132:133], s[92:93], v[236:237] op_sel_hi:[1,0,0]
	v_exp_f32_e32 v52, v52
	v_exp_f32_e32 v53, v53
	v_exp_f32_e32 v164, v164
	v_exp_f32_e32 v165, v165
	v_pk_fma_f32 v[246:247], v[238:239], v[246:247], s[96:97] op_sel_hi:[1,1,0]
	v_pk_fma_f32 v[134:135], v[132:133], v[134:135], s[96:97] op_sel_hi:[1,1,0]
	v_pk_fma_f32 v[246:247], v[238:239], v[246:247], s[0:1] op_sel_hi:[1,1,0]
	v_pk_fma_f32 v[134:135], v[132:133], v[134:135], s[0:1] op_sel_hi:[1,1,0]
	v_pk_fma_f32 v[246:247], v[238:239], v[246:247], s[4:5] op_sel_hi:[1,1,0]
	v_pk_fma_f32 v[134:135], v[132:133], v[134:135], s[4:5] op_sel_hi:[1,1,0]
	v_pk_mul_f32 v[246:247], v[238:239], v[246:247]
	v_pk_mul_f32 v[134:135], v[132:133], v[134:135]
	v_max_f32_e32 v238, 0, v124
	v_max_f32_e32 v239, 0, v125
	v_max_f32_e32 v132, 0, v126
	v_max_f32_e32 v133, 0, v127
	v_pk_mul_f32 v[246:247], v[52:53], v[246:247]
	v_pk_mul_f32 v[134:135], v[164:165], v[134:135]
	v_pk_fma_f32 v[52:53], v[212:213], v[246:247], v[238:239] neg_lo:[1,0,0] neg_hi:[1,0,0]
	v_pk_fma_f32 v[164:165], v[54:55], v[134:135], v[132:133] neg_lo:[1,0,0] neg_hi:[1,0,0]
	v_pk_mul_f32 v[246:247], v[52:53], v[116:117]
	v_pk_mul_f32 v[134:135], v[164:165], v[118:119]
	v_cvt_pk_bf16_f32 v48, v246, v247
	v_cvt_pk_bf16_f32 v49, v134, v135
	v_add_u32_e32 v235, 3, v228
	v_cmp_gt_i32_e32 vcc, 0x4000, v235
	s_nop 1
	v_cndmask_b32_e32 v245, v222, v221, vcc
	v_and_b32_e32 v235, v235, v245
	v_cmp_eq_u32_e64 s[34:35], 0, v235
	v_cmp_eq_u32_e64 s[36:37], v235, v245
	s_nop 1
	v_cndmask_b32_e64 v112, v112, 0, s[34:35]
	v_cndmask_b32_e64 v113, v113, 0, s[34:35]
	v_cndmask_b32_e64 v114, v114, 0, s[34:35]
	v_cndmask_b32_e64 v115, v115, 0, s[34:35]
	v_cndmask_b32_e64 v100, v100, 0, s[34:35]
	v_cndmask_b32_e64 v101, v101, 0, s[34:35]
	v_cndmask_b32_e64 v102, v102, 0, s[34:35]
	v_cndmask_b32_e64 v103, v103, 0, s[34:35]
	v_pk_fma_f32 v[112:113], v[176:177], v[112:113], v[200:201]
	v_pk_fma_f32 v[114:115], v[178:179], v[114:115], v[202:203]
	v_pk_fma_f32 v[100:101], v[180:181], v[100:101], v[204:205]
	v_pk_fma_f32 v[102:103], v[182:183], v[102:103], v[206:207]
	v_pk_fma_f32 v[112:113], v[60:61], v[184:185], v[112:113]
	v_pk_fma_f32 v[114:115], v[62:63], v[186:187], v[114:115]
	v_pk_fma_f32 v[100:101], v[44:45], v[188:189], v[100:101]
	v_pk_fma_f32 v[102:103], v[46:47], v[190:191], v[102:103]
	s_mov_b64 s[30:31], exec
	s_andn2_b64 exec, exec, s[36:37]
	v_pk_fma_f32 v[112:113], v[192:193], v[152:153], v[112:113]
	v_pk_fma_f32 v[114:115], v[194:195], v[154:155], v[114:115]
	v_pk_fma_f32 v[100:101], v[196:197], v[156:157], v[100:101]
	v_pk_fma_f32 v[102:103], v[198:199], v[158:159], v[102:103]
	s_mov_b64 exec, s[30:31]
	v_and_b32_e32 v212, 0x7fffffff, v112
	v_and_b32_e32 v213, 0x7fffffff, v113
	v_and_b32_e32 v118, 0x7fffffff, v114
	v_and_b32_e32 v119, 0x7fffffff, v115
	v_pk_fma_f32 v[238:239], v[212:213], s[90:91], 1.0 op_sel_hi:[1,0,0]
	v_pk_fma_f32 v[124:125], v[118:119], s[90:91], 1.0 op_sel_hi:[1,0,0]
	v_pk_mul_f32 v[116:117], v[112:113], v[112:113]
	v_pk_mul_f32 v[132:133], v[114:115], v[114:115]
	v_rcp_f32_e32 v238, v238
	v_rcp_f32_e32 v239, v239
	v_rcp_f32_e32 v124, v124
	v_rcp_f32_e32 v125, v125
	v_pk_mul_f32 v[116:117], v[116:117], s[44:45] op_sel_hi:[1,0]
	v_pk_mul_f32 v[132:133], v[132:133], s[44:45] op_sel_hi:[1,0]
	v_pk_fma_f32 v[246:247], v[238:239], s[92:93], v[236:237] op_sel_hi:[1,0,0]
	v_pk_fma_f32 v[126:127], v[124:125], s[92:93], v[236:237] op_sel_hi:[1,0,0]
	v_exp_f32_e32 v116, v116
	v_exp_f32_e32 v117, v117
	v_exp_f32_e32 v132, v132
	v_exp_f32_e32 v133, v133
	v_pk_fma_f32 v[246:247], v[238:239], v[246:247], s[96:97] op_sel_hi:[1,1,0]
	v_pk_fma_f32 v[126:127], v[124:125], v[126:127], s[96:97] op_sel_hi:[1,1,0]
	v_pk_fma_f32 v[246:247], v[238:239], v[246:247], s[0:1] op_sel_hi:[1,1,0]
	v_pk_fma_f32 v[126:127], v[124:125], v[126:127], s[0:1] op_sel_hi:[1,1,0]
	v_pk_fma_f32 v[246:247], v[238:239], v[246:247], s[4:5] op_sel_hi:[1,1,0]
	v_pk_fma_f32 v[126:127], v[124:125], v[126:127], s[4:5] op_sel_hi:[1,1,0]
	v_pk_mul_f32 v[246:247], v[238:239], v[246:247]
	v_pk_mul_f32 v[126:127], v[124:125], v[126:127]
	v_max_f32_e32 v238, 0, v112
	v_max_f32_e32 v239, 0, v113
	v_max_f32_e32 v124, 0, v114
	v_max_f32_e32 v125, 0, v115
	v_pk_mul_f32 v[246:247], v[116:117], v[246:247]
	v_pk_mul_f32 v[126:127], v[132:133], v[126:127]
	v_pk_fma_f32 v[116:117], v[212:213], v[246:247], v[238:239] neg_lo:[1,0,0] neg_hi:[1,0,0]
	v_pk_fma_f32 v[132:133], v[118:119], v[126:127], v[124:125] neg_lo:[1,0,0] neg_hi:[1,0,0]
	v_pk_mul_f32 v[246:247], v[116:117], v[100:101]
	v_pk_mul_f32 v[126:127], v[132:133], v[102:103]
	v_cvt_pk_bf16_f32 v52, v246, v247
	v_cvt_pk_bf16_f32 v53, v126, v127
	ds_read_b128 v[44:47], v232 offset:0
	ds_read_b128 v[60:63], v232 offset:512
	ds_read_b128 v[100:103], v234 offset:0
	ds_read_b128 v[112:115], v234 offset:512
	s_waitcnt lgkmcnt(0)
	v_mov_b32_dpp v44, v4 row_shr:1 row_mask:0xf bank_mask:0xf
	v_mov_b32_dpp v45, v5 row_shr:1 row_mask:0xf bank_mask:0xf
	v_mov_b32_dpp v46, v6 row_shr:1 row_mask:0xf bank_mask:0xf
	v_mov_b32_dpp v47, v7 row_shr:1 row_mask:0xf bank_mask:0xf
	v_mov_b32_dpp v60, v32 row_shr:1 row_mask:0xf bank_mask:0xf
	v_mov_b32_dpp v61, v33 row_shr:1 row_mask:0xf bank_mask:0xf
	v_mov_b32_dpp v62, v34 row_shr:1 row_mask:0xf bank_mask:0xf
	v_mov_b32_dpp v63, v35 row_shr:1 row_mask:0xf bank_mask:0xf
	v_mov_b32_dpp v100, v12 row_shl:1 row_mask:0xf bank_mask:0xf
	v_mov_b32_dpp v101, v13 row_shl:1 row_mask:0xf bank_mask:0xf
	v_mov_b32_dpp v102, v14 row_shl:1 row_mask:0xf bank_mask:0xf
	v_mov_b32_dpp v103, v15 row_shl:1 row_mask:0xf bank_mask:0xf
	v_mov_b32_dpp v112, v40 row_shl:1 row_mask:0xf bank_mask:0xf
	v_mov_b32_dpp v113, v41 row_shl:1 row_mask:0xf bank_mask:0xf
	v_mov_b32_dpp v114, v42 row_shl:1 row_mask:0xf bank_mask:0xf
	v_mov_b32_dpp v115, v43 row_shl:1 row_mask:0xf bank_mask:0xf
	v_add_u32_e32 v235, 128, v228
	v_cmp_gt_i32_e32 vcc, 0x4000, v235
	s_nop 1
	v_cndmask_b32_e32 v245, v222, v221, vcc
	v_and_b32_e32 v235, v235, v245
	v_cmp_eq_u32_e64 s[34:35], 0, v235
	v_cmp_eq_u32_e64 s[36:37], v235, v245
	s_nop 1
	v_cndmask_b32_e64 v44, v44, 0, s[34:35]
	v_cndmask_b32_e64 v45, v45, 0, s[34:35]
	v_cndmask_b32_e64 v46, v46, 0, s[34:35]
	v_cndmask_b32_e64 v47, v47, 0, s[34:35]
	v_cndmask_b32_e64 v60, v60, 0, s[34:35]
	v_cndmask_b32_e64 v61, v61, 0, s[34:35]
	v_cndmask_b32_e64 v62, v62, 0, s[34:35]
	v_cndmask_b32_e64 v63, v63, 0, s[34:35]
	v_pk_fma_f32 v[44:45], v[176:177], v[44:45], v[200:201]
	v_pk_fma_f32 v[46:47], v[178:179], v[46:47], v[202:203]
	v_pk_fma_f32 v[60:61], v[180:181], v[60:61], v[204:205]
	v_pk_fma_f32 v[62:63], v[182:183], v[62:63], v[206:207]
	v_pk_fma_f32 v[44:45], v[12:13], v[184:185], v[44:45]
	v_pk_fma_f32 v[46:47], v[14:15], v[186:187], v[46:47]
	v_pk_fma_f32 v[60:61], v[40:41], v[188:189], v[60:61]
	v_pk_fma_f32 v[62:63], v[42:43], v[190:191], v[62:63]
	s_mov_b64 s[30:31], exec
	s_andn2_b64 exec, exec, s[36:37]
	v_pk_fma_f32 v[44:45], v[192:193], v[92:93], v[44:45]
	v_pk_fma_f32 v[46:47], v[194:195], v[94:95], v[46:47]
	v_pk_fma_f32 v[60:61], v[196:197], v[84:85], v[60:61]
	v_pk_fma_f32 v[62:63], v[198:199], v[86:87], v[62:63]
	s_mov_b64 exec, s[30:31]
	v_and_b32_e32 v212, 0x7fffffff, v44
	v_and_b32_e32 v213, 0x7fffffff, v45
	v_and_b32_e32 v126, 0x7fffffff, v46
	v_and_b32_e32 v127, 0x7fffffff, v47
	v_pk_fma_f32 v[238:239], v[212:213], s[90:91], 1.0 op_sel_hi:[1,0,0]
	v_pk_fma_f32 v[132:133], v[126:127], s[90:91], 1.0 op_sel_hi:[1,0,0]
	v_pk_mul_f32 v[124:125], v[44:45], v[44:45]
	v_pk_mul_f32 v[152:153], v[46:47], v[46:47]
	v_rcp_f32_e32 v238, v238
	v_rcp_f32_e32 v239, v239
	v_rcp_f32_e32 v132, v132
	v_rcp_f32_e32 v133, v133
	v_pk_mul_f32 v[124:125], v[124:125], s[44:45] op_sel_hi:[1,0]
	v_pk_mul_f32 v[152:153], v[152:153], s[44:45] op_sel_hi:[1,0]
	v_pk_fma_f32 v[246:247], v[238:239], s[92:93], v[236:237] op_sel_hi:[1,0,0]
	v_pk_fma_f32 v[134:135], v[132:133], s[92:93], v[236:237] op_sel_hi:[1,0,0]
	v_exp_f32_e32 v124, v124
	v_exp_f32_e32 v125, v125
	v_exp_f32_e32 v152, v152
	v_exp_f32_e32 v153, v153
	v_pk_fma_f32 v[246:247], v[238:239], v[246:247], s[96:97] op_sel_hi:[1,1,0]
	v_pk_fma_f32 v[134:135], v[132:133], v[134:135], s[96:97] op_sel_hi:[1,1,0]
	v_pk_fma_f32 v[246:247], v[238:239], v[246:247], s[0:1] op_sel_hi:[1,1,0]
	v_pk_fma_f32 v[134:135], v[132:133], v[134:135], s[0:1] op_sel_hi:[1,1,0]
	v_pk_fma_f32 v[246:247], v[238:239], v[246:247], s[4:5] op_sel_hi:[1,1,0]
	v_pk_fma_f32 v[134:135], v[132:133], v[134:135], s[4:5] op_sel_hi:[1,1,0]
	v_pk_mul_f32 v[246:247], v[238:239], v[246:247]
	v_pk_mul_f32 v[134:135], v[132:133], v[134:135]
	v_max_f32_e32 v238, 0, v44
	v_max_f32_e32 v239, 0, v45
	v_max_f32_e32 v132, 0, v46
	v_max_f32_e32 v133, 0, v47
	v_pk_mul_f32 v[246:247], v[124:125], v[246:247]
	v_pk_mul_f32 v[134:135], v[152:153], v[134:135]
	v_pk_fma_f32 v[124:125], v[212:213], v[246:247], v[238:239] neg_lo:[1,0,0] neg_hi:[1,0,0]
	v_pk_fma_f32 v[152:153], v[126:127], v[134:135], v[132:133] neg_lo:[1,0,0] neg_hi:[1,0,0]
	v_pk_mul_f32 v[246:247], v[124:125], v[60:61]
	v_pk_mul_f32 v[134:135], v[152:153], v[62:63]
	v_cvt_pk_bf16_f32 v116, v246, v247
	v_cvt_pk_bf16_f32 v117, v134, v135
	v_add_u32_e32 v235, 129, v228
	v_cmp_gt_i32_e32 vcc, 0x4000, v235
	s_nop 1
	v_cndmask_b32_e32 v245, v222, v221, vcc
	v_and_b32_e32 v235, v235, v245
	v_cmp_eq_u32_e64 s[34:35], 0, v235
	v_cmp_eq_u32_e64 s[36:37], v235, v245
	s_nop 1
	v_cndmask_b32_e64 v12, v12, 0, s[34:35]
	v_cndmask_b32_e64 v13, v13, 0, s[34:35]
	v_cndmask_b32_e64 v14, v14, 0, s[34:35]
	v_cndmask_b32_e64 v15, v15, 0, s[34:35]
	v_cndmask_b32_e64 v40, v40, 0, s[34:35]
	v_cndmask_b32_e64 v41, v41, 0, s[34:35]
	v_cndmask_b32_e64 v42, v42, 0, s[34:35]
	v_cndmask_b32_e64 v43, v43, 0, s[34:35]
	v_pk_fma_f32 v[12:13], v[176:177], v[12:13], v[200:201]
	v_pk_fma_f32 v[14:15], v[178:179], v[14:15], v[202:203]
	v_pk_fma_f32 v[40:41], v[180:181], v[40:41], v[204:205]
	v_pk_fma_f32 v[42:43], v[182:183], v[42:43], v[206:207]
	v_pk_fma_f32 v[12:13], v[92:93], v[184:185], v[12:13]
	v_pk_fma_f32 v[14:15], v[94:95], v[186:187], v[14:15]
	v_pk_fma_f32 v[40:41], v[84:85], v[188:189], v[40:41]
	v_pk_fma_f32 v[42:43], v[86:87], v[190:191], v[42:43]
	s_mov_b64 s[30:31], exec
	s_andn2_b64 exec, exec, s[36:37]
	v_pk_fma_f32 v[12:13], v[192:193], v[80:81], v[12:13]
	v_pk_fma_f32 v[14:15], v[194:195], v[82:83], v[14:15]
	v_pk_fma_f32 v[40:41], v[196:197], v[68:69], v[40:41]
	v_pk_fma_f32 v[42:43], v[198:199], v[70:71], v[42:43]
	s_mov_b64 exec, s[30:31]
	v_and_b32_e32 v212, 0x7fffffff, v12
	v_and_b32_e32 v213, 0x7fffffff, v13
	v_and_b32_e32 v62, 0x7fffffff, v14
	v_and_b32_e32 v63, 0x7fffffff, v15
	v_pk_fma_f32 v[238:239], v[212:213], s[90:91], 1.0 op_sel_hi:[1,0,0]
	v_pk_fma_f32 v[124:125], v[62:63], s[90:91], 1.0 op_sel_hi:[1,0,0]
	v_pk_mul_f32 v[60:61], v[12:13], v[12:13]
	v_pk_mul_f32 v[132:133], v[14:15], v[14:15]
	v_rcp_f32_e32 v238, v238
	v_rcp_f32_e32 v239, v239
	v_rcp_f32_e32 v124, v124
	v_rcp_f32_e32 v125, v125
	v_pk_mul_f32 v[60:61], v[60:61], s[44:45] op_sel_hi:[1,0]
	v_pk_mul_f32 v[132:133], v[132:133], s[44:45] op_sel_hi:[1,0]
	v_pk_fma_f32 v[246:247], v[238:239], s[92:93], v[236:237] op_sel_hi:[1,0,0]
	v_pk_fma_f32 v[126:127], v[124:125], s[92:93], v[236:237] op_sel_hi:[1,0,0]
	v_exp_f32_e32 v60, v60
	v_exp_f32_e32 v61, v61
	v_exp_f32_e32 v132, v132
	v_exp_f32_e32 v133, v133
	v_pk_fma_f32 v[246:247], v[238:239], v[246:247], s[96:97] op_sel_hi:[1,1,0]
	v_pk_fma_f32 v[126:127], v[124:125], v[126:127], s[96:97] op_sel_hi:[1,1,0]
	v_pk_fma_f32 v[246:247], v[238:239], v[246:247], s[0:1] op_sel_hi:[1,1,0]
	v_pk_fma_f32 v[126:127], v[124:125], v[126:127], s[0:1] op_sel_hi:[1,1,0]
	v_pk_fma_f32 v[246:247], v[238:239], v[246:247], s[4:5] op_sel_hi:[1,1,0]
	v_pk_fma_f32 v[126:127], v[124:125], v[126:127], s[4:5] op_sel_hi:[1,1,0]
	v_pk_mul_f32 v[246:247], v[238:239], v[246:247]
	v_pk_mul_f32 v[126:127], v[124:125], v[126:127]
	v_max_f32_e32 v238, 0, v12
	v_max_f32_e32 v239, 0, v13
	v_max_f32_e32 v124, 0, v14
	v_max_f32_e32 v125, 0, v15
	v_pk_mul_f32 v[246:247], v[60:61], v[246:247]
	v_pk_mul_f32 v[126:127], v[132:133], v[126:127]
	v_pk_fma_f32 v[60:61], v[212:213], v[246:247], v[238:239] neg_lo:[1,0,0] neg_hi:[1,0,0]
	v_pk_fma_f32 v[132:133], v[62:63], v[126:127], v[124:125] neg_lo:[1,0,0] neg_hi:[1,0,0]
	v_pk_mul_f32 v[246:247], v[60:61], v[40:41]
	v_pk_mul_f32 v[126:127], v[132:133], v[42:43]
	v_cvt_pk_bf16_f32 v44, v246, v247
	v_cvt_pk_bf16_f32 v45, v126, v127
	v_add_u32_e32 v235, 130, v228
	v_cmp_gt_i32_e32 vcc, 0x4000, v235
	s_nop 1
	v_cndmask_b32_e32 v245, v222, v221, vcc
	v_and_b32_e32 v235, v235, v245
	v_cmp_eq_u32_e64 s[34:35], 0, v235
	v_cmp_eq_u32_e64 s[36:37], v235, v245
	s_nop 1
	v_cndmask_b32_e64 v92, v92, 0, s[34:35]
	v_cndmask_b32_e64 v93, v93, 0, s[34:35]
	v_cndmask_b32_e64 v94, v94, 0, s[34:35]
	v_cndmask_b32_e64 v95, v95, 0, s[34:35]
	v_cndmask_b32_e64 v84, v84, 0, s[34:35]
	v_cndmask_b32_e64 v85, v85, 0, s[34:35]
	v_cndmask_b32_e64 v86, v86, 0, s[34:35]
	v_cndmask_b32_e64 v87, v87, 0, s[34:35]
	v_pk_fma_f32 v[92:93], v[176:177], v[92:93], v[200:201]
	v_pk_fma_f32 v[94:95], v[178:179], v[94:95], v[202:203]
	v_pk_fma_f32 v[84:85], v[180:181], v[84:85], v[204:205]
	v_pk_fma_f32 v[86:87], v[182:183], v[86:87], v[206:207]
	v_pk_fma_f32 v[92:93], v[80:81], v[184:185], v[92:93]
	v_pk_fma_f32 v[94:95], v[82:83], v[186:187], v[94:95]
	v_pk_fma_f32 v[84:85], v[68:69], v[188:189], v[84:85]
	v_pk_fma_f32 v[86:87], v[70:71], v[190:191], v[86:87]
	s_mov_b64 s[30:31], exec
	s_andn2_b64 exec, exec, s[36:37]
	v_pk_fma_f32 v[92:93], v[192:193], v[4:5], v[92:93]
	v_pk_fma_f32 v[94:95], v[194:195], v[6:7], v[94:95]
	v_pk_fma_f32 v[84:85], v[196:197], v[32:33], v[84:85]
	v_pk_fma_f32 v[86:87], v[198:199], v[34:35], v[86:87]
	s_mov_b64 exec, s[30:31]
	ds_read_b128 v[12:15], v231 offset:16
	ds_read_b128 v[40:43], v231 offset:528
	ds_read_b128 v[60:63], v233 offset:16
	ds_read_b128 v[124:127], v233 offset:528
	v_and_b32_e32 v212, 0x7fffffff, v92
	v_and_b32_e32 v213, 0x7fffffff, v93
	v_and_b32_e32 v154, 0x7fffffff, v94
	v_and_b32_e32 v155, 0x7fffffff, v95
	v_pk_fma_f32 v[238:239], v[212:213], s[90:91], 1.0 op_sel_hi:[1,0,0]
	v_pk_fma_f32 v[156:157], v[154:155], s[90:91], 1.0 op_sel_hi:[1,0,0]
	v_pk_mul_f32 v[152:153], v[92:93], v[92:93]
	v_pk_mul_f32 v[164:165], v[94:95], v[94:95]
	v_rcp_f32_e32 v238, v238
	v_rcp_f32_e32 v239, v239
	v_rcp_f32_e32 v156, v156
	v_rcp_f32_e32 v157, v157
	v_pk_mul_f32 v[152:153], v[152:153], s[44:45] op_sel_hi:[1,0]
	v_pk_mul_f32 v[164:165], v[164:165], s[44:45] op_sel_hi:[1,0]
	v_pk_fma_f32 v[246:247], v[238:239], s[92:93], v[236:237] op_sel_hi:[1,0,0]
	v_pk_fma_f32 v[158:159], v[156:157], s[92:93], v[236:237] op_sel_hi:[1,0,0]
	v_exp_f32_e32 v152, v152
	v_exp_f32_e32 v153, v153
	v_exp_f32_e32 v164, v164
	v_exp_f32_e32 v165, v165
	v_pk_fma_f32 v[246:247], v[238:239], v[246:247], s[96:97] op_sel_hi:[1,1,0]
	v_pk_fma_f32 v[158:159], v[156:157], v[158:159], s[96:97] op_sel_hi:[1,1,0]
	v_pk_fma_f32 v[246:247], v[238:239], v[246:247], s[0:1] op_sel_hi:[1,1,0]
	v_pk_fma_f32 v[158:159], v[156:157], v[158:159], s[0:1] op_sel_hi:[1,1,0]
	v_pk_fma_f32 v[246:247], v[238:239], v[246:247], s[4:5] op_sel_hi:[1,1,0]
	v_pk_fma_f32 v[158:159], v[156:157], v[158:159], s[4:5] op_sel_hi:[1,1,0]
	v_pk_mul_f32 v[246:247], v[238:239], v[246:247]
	v_pk_mul_f32 v[158:159], v[156:157], v[158:159]
	v_max_f32_e32 v238, 0, v92
	v_max_f32_e32 v239, 0, v93
	v_max_f32_e32 v156, 0, v94
	v_max_f32_e32 v157, 0, v95
	v_pk_mul_f32 v[246:247], v[152:153], v[246:247]
	v_pk_mul_f32 v[158:159], v[164:165], v[158:159]
	v_pk_fma_f32 v[152:153], v[212:213], v[246:247], v[238:239] neg_lo:[1,0,0] neg_hi:[1,0,0]
	v_pk_fma_f32 v[164:165], v[154:155], v[158:159], v[156:157] neg_lo:[1,0,0] neg_hi:[1,0,0]
	v_pk_mul_f32 v[246:247], v[152:153], v[84:85]
	v_pk_mul_f32 v[158:159], v[164:165], v[86:87]
	v_cvt_pk_bf16_f32 v132, v246, v247
	v_cvt_pk_bf16_f32 v133, v158, v159
	v_add_u32_e32 v235, 131, v228
	v_cmp_gt_i32_e32 vcc, 0x4000, v235
	s_nop 1
	v_cndmask_b32_e32 v245, v222, v221, vcc
	v_and_b32_e32 v235, v235, v245
	v_cmp_eq_u32_e64 s[34:35], 0, v235
	v_cmp_eq_u32_e64 s[36:37], v235, v245
	s_nop 1
	v_cndmask_b32_e64 v80, v80, 0, s[34:35]
	v_cndmask_b32_e64 v81, v81, 0, s[34:35]
	v_cndmask_b32_e64 v82, v82, 0, s[34:35]
	v_cndmask_b32_e64 v83, v83, 0, s[34:35]
	v_cndmask_b32_e64 v68, v68, 0, s[34:35]
	v_cndmask_b32_e64 v69, v69, 0, s[34:35]
	v_cndmask_b32_e64 v70, v70, 0, s[34:35]
	v_cndmask_b32_e64 v71, v71, 0, s[34:35]
	v_pk_fma_f32 v[80:81], v[176:177], v[80:81], v[200:201]
	v_pk_fma_f32 v[82:83], v[178:179], v[82:83], v[202:203]
	v_pk_fma_f32 v[68:69], v[180:181], v[68:69], v[204:205]
	v_pk_fma_f32 v[70:71], v[182:183], v[70:71], v[206:207]
	v_pk_fma_f32 v[80:81], v[4:5], v[184:185], v[80:81]
	v_pk_fma_f32 v[82:83], v[6:7], v[186:187], v[82:83]
	v_pk_fma_f32 v[68:69], v[32:33], v[188:189], v[68:69]
	v_pk_fma_f32 v[70:71], v[34:35], v[190:191], v[70:71]
	s_mov_b64 s[30:31], exec
	s_andn2_b64 exec, exec, s[36:37]
	v_pk_fma_f32 v[80:81], v[192:193], v[100:101], v[80:81]
	v_pk_fma_f32 v[82:83], v[194:195], v[102:103], v[82:83]
	v_pk_fma_f32 v[68:69], v[196:197], v[112:113], v[68:69]
	v_pk_fma_f32 v[70:71], v[198:199], v[114:115], v[70:71]
	s_mov_b64 exec, s[30:31]
	v_and_b32_e32 v212, 0x7fffffff, v80
	v_and_b32_e32 v213, 0x7fffffff, v81
	v_and_b32_e32 v94, 0x7fffffff, v82
	v_and_b32_e32 v95, 0x7fffffff, v83
	v_pk_fma_f32 v[238:239], v[212:213], s[90:91], 1.0 op_sel_hi:[1,0,0]
	v_pk_fma_f32 v[152:153], v[94:95], s[90:91], 1.0 op_sel_hi:[1,0,0]
	v_pk_mul_f32 v[92:93], v[80:81], v[80:81]
	v_pk_mul_f32 v[156:157], v[82:83], v[82:83]
	v_rcp_f32_e32 v238, v238
	v_rcp_f32_e32 v239, v239
	v_rcp_f32_e32 v152, v152
	v_rcp_f32_e32 v153, v153
	v_pk_mul_f32 v[92:93], v[92:93], s[44:45] op_sel_hi:[1,0]
	v_pk_mul_f32 v[156:157], v[156:157], s[44:45] op_sel_hi:[1,0]
	v_pk_fma_f32 v[246:247], v[238:239], s[92:93], v[236:237] op_sel_hi:[1,0,0]
	v_pk_fma_f32 v[154:155], v[152:153], s[92:93], v[236:237] op_sel_hi:[1,0,0]
	v_exp_f32_e32 v92, v92
	v_exp_f32_e32 v93, v93
	v_exp_f32_e32 v156, v156
	v_exp_f32_e32 v157, v157
	v_pk_fma_f32 v[246:247], v[238:239], v[246:247], s[96:97] op_sel_hi:[1,1,0]
	v_pk_fma_f32 v[154:155], v[152:153], v[154:155], s[96:97] op_sel_hi:[1,1,0]
	v_pk_fma_f32 v[246:247], v[238:239], v[246:247], s[0:1] op_sel_hi:[1,1,0]
	v_pk_fma_f32 v[154:155], v[152:153], v[154:155], s[0:1] op_sel_hi:[1,1,0]
	v_pk_fma_f32 v[246:247], v[238:239], v[246:247], s[4:5] op_sel_hi:[1,1,0]
	v_pk_fma_f32 v[154:155], v[152:153], v[154:155], s[4:5] op_sel_hi:[1,1,0]
	v_pk_mul_f32 v[246:247], v[238:239], v[246:247]
	v_pk_mul_f32 v[154:155], v[152:153], v[154:155]
	v_max_f32_e32 v238, 0, v80
	v_max_f32_e32 v239, 0, v81
	v_max_f32_e32 v152, 0, v82
	v_max_f32_e32 v153, 0, v83
	v_pk_mul_f32 v[246:247], v[92:93], v[246:247]
	v_pk_mul_f32 v[154:155], v[156:157], v[154:155]
	v_pk_fma_f32 v[92:93], v[212:213], v[246:247], v[238:239] neg_lo:[1,0,0] neg_hi:[1,0,0]
	v_pk_fma_f32 v[156:157], v[94:95], v[154:155], v[152:153] neg_lo:[1,0,0] neg_hi:[1,0,0]
	v_pk_mul_f32 v[246:247], v[92:93], v[68:69]
	v_pk_mul_f32 v[154:155], v[156:157], v[70:71]
	v_cvt_pk_bf16_f32 v84, v246, v247
	v_cvt_pk_bf16_f32 v85, v154, v155
	ds_read_b128 v[4:7], v226 offset:16
	ds_read_b128 v[32:35], v226 offset:528
	ds_read_b128 v[68:71], v226 offset:1040
	ds_read_b128 v[80:83], v226 offset:1552
	ds_read_b128 v[92:95], v226 offset:2064
	ds_read_b128 v[100:103], v226 offset:2576
	ds_read_b128 v[112:115], v226 offset:3088
	ds_read_b128 v[152:155], v226 offset:3600
	s_waitcnt lgkmcnt(0)
	v_mov_b32_dpp v12, v16 row_shr:1 row_mask:0xf bank_mask:0xf
	v_mov_b32_dpp v13, v17 row_shr:1 row_mask:0xf bank_mask:0xf
	v_mov_b32_dpp v14, v18 row_shr:1 row_mask:0xf bank_mask:0xf
	v_mov_b32_dpp v15, v19 row_shr:1 row_mask:0xf bank_mask:0xf
	v_mov_b32_dpp v40, v20 row_shr:1 row_mask:0xf bank_mask:0xf
	v_mov_b32_dpp v41, v21 row_shr:1 row_mask:0xf bank_mask:0xf
	v_mov_b32_dpp v42, v22 row_shr:1 row_mask:0xf bank_mask:0xf
	v_mov_b32_dpp v43, v23 row_shr:1 row_mask:0xf bank_mask:0xf
	v_mov_b32_dpp v60, v24 row_shl:1 row_mask:0xf bank_mask:0xf
	v_mov_b32_dpp v61, v25 row_shl:1 row_mask:0xf bank_mask:0xf
	v_mov_b32_dpp v62, v26 row_shl:1 row_mask:0xf bank_mask:0xf
	v_mov_b32_dpp v63, v27 row_shl:1 row_mask:0xf bank_mask:0xf
	v_mov_b32_dpp v124, v28 row_shl:1 row_mask:0xf bank_mask:0xf
	v_mov_b32_dpp v125, v29 row_shl:1 row_mask:0xf bank_mask:0xf
	v_mov_b32_dpp v126, v30 row_shl:1 row_mask:0xf bank_mask:0xf
	v_mov_b32_dpp v127, v31 row_shl:1 row_mask:0xf bank_mask:0xf
	v_mov_b32_e32 v235, v228
	v_cmp_gt_i32_e32 vcc, 0x4000, v235
	s_nop 1
	v_cndmask_b32_e32 v245, v222, v221, vcc
	v_and_b32_e32 v235, v235, v245
	v_cmp_eq_u32_e64 s[34:35], 0, v235
	v_cmp_eq_u32_e64 s[36:37], v235, v245
	s_nop 1
	v_cndmask_b32_e64 v12, v12, 0, s[34:35]
	v_cndmask_b32_e64 v13, v13, 0, s[34:35]
	v_cndmask_b32_e64 v14, v14, 0, s[34:35]
	v_cndmask_b32_e64 v15, v15, 0, s[34:35]
	v_cndmask_b32_e64 v40, v40, 0, s[34:35]
	v_cndmask_b32_e64 v41, v41, 0, s[34:35]
	v_cndmask_b32_e64 v42, v42, 0, s[34:35]
	v_cndmask_b32_e64 v43, v43, 0, s[34:35]
	v_pk_fma_f32 v[12:13], v[4:5], v[12:13], v[112:113]
	v_pk_fma_f32 v[14:15], v[6:7], v[14:15], v[114:115]
	v_pk_fma_f32 v[40:41], v[32:33], v[40:41], v[152:153]
	v_pk_fma_f32 v[42:43], v[34:35], v[42:43], v[154:155]
	v_pk_fma_f32 v[12:13], v[24:25], v[68:69], v[12:13]
	v_pk_fma_f32 v[14:15], v[26:27], v[70:71], v[14:15]
	v_pk_fma_f32 v[40:41], v[28:29], v[80:81], v[40:41]
	v_pk_fma_f32 v[42:43], v[30:31], v[82:83], v[42:43]
	s_mov_b64 s[30:31], exec
	s_andn2_b64 exec, exec, s[36:37]
	v_pk_fma_f32 v[12:13], v[92:93], v[120:121], v[12:13]
	v_pk_fma_f32 v[14:15], v[94:95], v[122:123], v[14:15]
	v_pk_fma_f32 v[40:41], v[100:101], v[108:109], v[40:41]
	v_pk_fma_f32 v[42:43], v[102:103], v[110:111], v[42:43]
	s_mov_b64 exec, s[30:31]
	v_and_b32_e32 v212, 0x7fffffff, v12
	v_and_b32_e32 v213, 0x7fffffff, v13
	v_and_b32_e32 v158, 0x7fffffff, v14
	v_and_b32_e32 v159, 0x7fffffff, v15
	v_pk_fma_f32 v[238:239], v[212:213], s[90:91], 1.0 op_sel_hi:[1,0,0]
	v_pk_fma_f32 v[164:165], v[158:159], s[90:91], 1.0 op_sel_hi:[1,0,0]
	v_pk_mul_f32 v[156:157], v[12:13], v[12:13]
	v_pk_mul_f32 v[168:169], v[14:15], v[14:15]
	v_rcp_f32_e32 v238, v238
	v_rcp_f32_e32 v239, v239
	v_rcp_f32_e32 v164, v164
	v_rcp_f32_e32 v165, v165
	v_pk_mul_f32 v[156:157], v[156:157], s[44:45] op_sel_hi:[1,0]
	v_pk_mul_f32 v[168:169], v[168:169], s[44:45] op_sel_hi:[1,0]
	v_pk_fma_f32 v[246:247], v[238:239], s[92:93], v[236:237] op_sel_hi:[1,0,0]
	v_pk_fma_f32 v[166:167], v[164:165], s[92:93], v[236:237] op_sel_hi:[1,0,0]
	v_exp_f32_e32 v156, v156
	v_exp_f32_e32 v157, v157
	v_exp_f32_e32 v168, v168
	v_exp_f32_e32 v169, v169
	v_pk_fma_f32 v[246:247], v[238:239], v[246:247], s[96:97] op_sel_hi:[1,1,0]
	v_pk_fma_f32 v[166:167], v[164:165], v[166:167], s[96:97] op_sel_hi:[1,1,0]
	v_pk_fma_f32 v[246:247], v[238:239], v[246:247], s[0:1] op_sel_hi:[1,1,0]
	v_pk_fma_f32 v[166:167], v[164:165], v[166:167], s[0:1] op_sel_hi:[1,1,0]
	v_pk_fma_f32 v[246:247], v[238:239], v[246:247], s[4:5] op_sel_hi:[1,1,0]
	v_pk_fma_f32 v[166:167], v[164:165], v[166:167], s[4:5] op_sel_hi:[1,1,0]
	v_pk_mul_f32 v[246:247], v[238:239], v[246:247]
	v_pk_mul_f32 v[166:167], v[164:165], v[166:167]
	v_max_f32_e32 v238, 0, v12
	v_max_f32_e32 v239, 0, v13
	v_max_f32_e32 v164, 0, v14
	v_max_f32_e32 v165, 0, v15
	v_pk_mul_f32 v[246:247], v[156:157], v[246:247]
	v_pk_mul_f32 v[166:167], v[168:169], v[166:167]
	v_pk_fma_f32 v[156:157], v[212:213], v[246:247], v[238:239] neg_lo:[1,0,0] neg_hi:[1,0,0]
	v_pk_fma_f32 v[168:169], v[158:159], v[166:167], v[164:165] neg_lo:[1,0,0] neg_hi:[1,0,0]
	v_pk_mul_f32 v[246:247], v[156:157], v[40:41]
	v_pk_mul_f32 v[166:167], v[168:169], v[42:43]
	v_cvt_pk_bf16_f32 v162, v246, v247
	v_cvt_pk_bf16_f32 v163, v166, v167
	v_add_u32_e32 v235, -1, v227
	v_mov_b32_e32 v245, v228
	v_cmp_gt_u32_e64 s[38:39], s64, v235
	v_cmp_gt_u32_e32 vcc, s88, v245
	v_mov_b32_e32 v235, v230
	s_and_b64 s[38:39], s[38:39], vcc
	s_and_saveexec_b64 s[30:31], s[38:39]
	global_store_dwordx4 v235, v[160:163], s[50:51]
	s_mov_b64 exec, s[30:31]
	s_nop 1
	v_add_u32_e32 v235, 1, v228
	v_cmp_gt_i32_e32 vcc, 0x4000, v235
	s_nop 1
	v_cndmask_b32_e32 v245, v222, v221, vcc
	v_and_b32_e32 v235, v235, v245
	v_cmp_eq_u32_e64 s[34:35], 0, v235
	v_cmp_eq_u32_e64 s[36:37], v235, v245
	s_nop 1
	v_cndmask_b32_e64 v24, v24, 0, s[34:35]
	v_cndmask_b32_e64 v25, v25, 0, s[34:35]
	v_cndmask_b32_e64 v26, v26, 0, s[34:35]
	v_cndmask_b32_e64 v27, v27, 0, s[34:35]
	v_cndmask_b32_e64 v28, v28, 0, s[34:35]
	v_cndmask_b32_e64 v29, v29, 0, s[34:35]
	v_cndmask_b32_e64 v30, v30, 0, s[34:35]
	v_cndmask_b32_e64 v31, v31, 0, s[34:35]
	v_pk_fma_f32 v[24:25], v[4:5], v[24:25], v[112:113]
	v_pk_fma_f32 v[26:27], v[6:7], v[26:27], v[114:115]
	v_pk_fma_f32 v[28:29], v[32:33], v[28:29], v[152:153]
	v_pk_fma_f32 v[30:31], v[34:35], v[30:31], v[154:155]
	v_pk_fma_f32 v[24:25], v[120:121], v[68:69], v[24:25]
	v_pk_fma_f32 v[26:27], v[122:123], v[70:71], v[26:27]
	v_pk_fma_f32 v[28:29], v[108:109], v[80:81], v[28:29]
	v_pk_fma_f32 v[30:31], v[110:111], v[82:83], v[30:31]
	s_mov_b64 s[30:31], exec
	s_andn2_b64 exec, exec, s[36:37]
	v_pk_fma_f32 v[24:25], v[92:93], v[104:105], v[24:25]
	v_pk_fma_f32 v[26:27], v[94:95], v[106:107], v[26:27]
	v_pk_fma_f32 v[28:29], v[100:101], v[96:97], v[28:29]
	v_pk_fma_f32 v[30:31], v[102:103], v[98:99], v[30:31]
	s_mov_b64 exec, s[30:31]
	v_and_b32_e32 v212, 0x7fffffff, v24
	v_and_b32_e32 v213, 0x7fffffff, v25
	v_and_b32_e32 v14, 0x7fffffff, v26
	v_and_b32_e32 v15, 0x7fffffff, v27
	v_pk_fma_f32 v[238:239], v[212:213], s[90:91], 1.0 op_sel_hi:[1,0,0]
	v_pk_fma_f32 v[40:41], v[14:15], s[90:91], 1.0 op_sel_hi:[1,0,0]
	v_pk_mul_f32 v[12:13], v[24:25], v[24:25]
	v_pk_mul_f32 v[156:157], v[26:27], v[26:27]
	v_rcp_f32_e32 v238, v238
	v_rcp_f32_e32 v239, v239
	v_rcp_f32_e32 v40, v40
	v_rcp_f32_e32 v41, v41
	v_pk_mul_f32 v[12:13], v[12:13], s[44:45] op_sel_hi:[1,0]
	v_pk_mul_f32 v[156:157], v[156:157], s[44:45] op_sel_hi:[1,0]
	v_pk_fma_f32 v[246:247], v[238:239], s[92:93], v[236:237] op_sel_hi:[1,0,0]
	v_pk_fma_f32 v[42:43], v[40:41], s[92:93], v[236:237] op_sel_hi:[1,0,0]
	v_exp_f32_e32 v12, v12
	v_exp_f32_e32 v13, v13
	v_exp_f32_e32 v156, v156
	v_exp_f32_e32 v157, v157
	v_pk_fma_f32 v[246:247], v[238:239], v[246:247], s[96:97] op_sel_hi:[1,1,0]
	v_pk_fma_f32 v[42:43], v[40:41], v[42:43], s[96:97] op_sel_hi:[1,1,0]
	v_pk_fma_f32 v[246:247], v[238:239], v[246:247], s[0:1] op_sel_hi:[1,1,0]
	v_pk_fma_f32 v[42:43], v[40:41], v[42:43], s[0:1] op_sel_hi:[1,1,0]
	v_pk_fma_f32 v[246:247], v[238:239], v[246:247], s[4:5] op_sel_hi:[1,1,0]
	v_pk_fma_f32 v[42:43], v[40:41], v[42:43], s[4:5] op_sel_hi:[1,1,0]
	v_pk_mul_f32 v[246:247], v[238:239], v[246:247]
	v_pk_mul_f32 v[42:43], v[40:41], v[42:43]
	v_max_f32_e32 v238, 0, v24
	v_max_f32_e32 v239, 0, v25
	v_max_f32_e32 v40, 0, v26
	v_max_f32_e32 v41, 0, v27
	v_pk_mul_f32 v[246:247], v[12:13], v[246:247]
	v_pk_mul_f32 v[42:43], v[156:157], v[42:43]
	v_pk_fma_f32 v[12:13], v[212:213], v[246:247], v[238:239] neg_lo:[1,0,0] neg_hi:[1,0,0]
	v_pk_fma_f32 v[156:157], v[14:15], v[42:43], v[40:41] neg_lo:[1,0,0] neg_hi:[1,0,0]
	v_pk_mul_f32 v[246:247], v[12:13], v[28:29]
	v_pk_mul_f32 v[42:43], v[156:157], v[30:31]
	v_cvt_pk_bf16_f32 v58, v246, v247
	v_cvt_pk_bf16_f32 v59, v42, v43
	v_add_u32_e32 v235, 0, v227
	v_add_u32_e32 v245, 1, v228
	v_cmp_gt_u32_e64 s[38:39], s64, v235
	v_cmp_gt_u32_e32 vcc, s88, v245
	v_add_u32_e32 v235, 5632, v230
	s_and_b64 s[38:39], s[38:39], vcc
	s_and_saveexec_b64 s[30:31], s[38:39]
	global_store_dwordx4 v235, v[56:59], s[50:51]
	s_mov_b64 exec, s[30:31]
	s_nop 1
	v_add_u32_e32 v235, 2, v228
	v_cmp_gt_i32_e32 vcc, 0x4000, v235
	s_nop 1
	v_cndmask_b32_e32 v245, v222, v221, vcc
	v_and_b32_e32 v235, v235, v245
	v_cmp_eq_u32_e64 s[34:35], 0, v235
	v_cmp_eq_u32_e64 s[36:37], v235, v245
	s_nop 1
	v_cndmask_b32_e64 v120, v120, 0, s[34:35]
	v_cndmask_b32_e64 v121, v121, 0, s[34:35]
	v_cndmask_b32_e64 v122, v122, 0, s[34:35]
	v_cndmask_b32_e64 v123, v123, 0, s[34:35]
	v_cndmask_b32_e64 v108, v108, 0, s[34:35]
	v_cndmask_b32_e64 v109, v109, 0, s[34:35]
	v_cndmask_b32_e64 v110, v110, 0, s[34:35]
	v_cndmask_b32_e64 v111, v111, 0, s[34:35]
	v_pk_fma_f32 v[120:121], v[4:5], v[120:121], v[112:113]
	v_pk_fma_f32 v[122:123], v[6:7], v[122:123], v[114:115]
	v_pk_fma_f32 v[108:109], v[32:33], v[108:109], v[152:153]
	v_pk_fma_f32 v[110:111], v[34:35], v[110:111], v[154:155]
	v_pk_fma_f32 v[120:121], v[104:105], v[68:69], v[120:121]
	v_pk_fma_f32 v[122:123], v[106:107], v[70:71], v[122:123]
	v_pk_fma_f32 v[108:109], v[96:97], v[80:81], v[108:109]
	v_pk_fma_f32 v[110:111], v[98:99], v[82:83], v[110:111]
	s_mov_b64 s[30:31], exec
	s_andn2_b64 exec, exec, s[36:37]
	v_pk_fma_f32 v[120:121], v[92:93], v[16:17], v[120:121]
	v_pk_fma_f32 v[122:123], v[94:95], v[18:19], v[122:123]
	v_pk_fma_f32 v[108:109], v[100:101], v[20:21], v[108:109]
	v_pk_fma_f32 v[110:111], v[102:103], v[22:23], v[110:111]
	s_mov_b64 exec, s[30:31]
	ds_read_b128 v[12:15], v232 offset:16
	ds_read_b128 v[24:27], v232 offset:528
	ds_read_b128 v[28:31], v234 offset:16
	ds_read_b128 v[40:43], v234 offset:528
	v_and_b32_e32 v212, 0x7fffffff, v120
	v_and_b32_e32 v213, 0x7fffffff, v121
	v_and_b32_e32 v58, 0x7fffffff, v122
	v_and_b32_e32 v59, 0x7fffffff, v123
	v_pk_fma_f32 v[238:239], v[212:213], s[90:91], 1.0 op_sel_hi:[1,0,0]
	v_pk_fma_f32 v[156:157], v[58:59], s[90:91], 1.0 op_sel_hi:[1,0,0]
	v_pk_mul_f32 v[56:57], v[120:121], v[120:121]
	v_pk_mul_f32 v[160:161], v[122:123], v[122:123]
	v_rcp_f32_e32 v238, v238
	v_rcp_f32_e32 v239, v239
	v_rcp_f32_e32 v156, v156
	v_rcp_f32_e32 v157, v157
	v_pk_mul_f32 v[56:57], v[56:57], s[44:45] op_sel_hi:[1,0]
	v_pk_mul_f32 v[160:161], v[160:161], s[44:45] op_sel_hi:[1,0]
	v_pk_fma_f32 v[246:247], v[238:239], s[92:93], v[236:237] op_sel_hi:[1,0,0]
	v_pk_fma_f32 v[158:159], v[156:157], s[92:93], v[236:237] op_sel_hi:[1,0,0]
	v_exp_f32_e32 v56, v56
	v_exp_f32_e32 v57, v57
	v_exp_f32_e32 v160, v160
	v_exp_f32_e32 v161, v161
	v_pk_fma_f32 v[246:247], v[238:239], v[246:247], s[96:97] op_sel_hi:[1,1,0]
	v_pk_fma_f32 v[158:159], v[156:157], v[158:159], s[96:97] op_sel_hi:[1,1,0]
	v_pk_fma_f32 v[246:247], v[238:239], v[246:247], s[0:1] op_sel_hi:[1,1,0]
	v_pk_fma_f32 v[158:159], v[156:157], v[158:159], s[0:1] op_sel_hi:[1,1,0]
	v_pk_fma_f32 v[246:247], v[238:239], v[246:247], s[4:5] op_sel_hi:[1,1,0]
	v_pk_fma_f32 v[158:159], v[156:157], v[158:159], s[4:5] op_sel_hi:[1,1,0]
	v_pk_mul_f32 v[246:247], v[238:239], v[246:247]
	v_pk_mul_f32 v[158:159], v[156:157], v[158:159]
	v_max_f32_e32 v238, 0, v120
	v_max_f32_e32 v239, 0, v121
	v_max_f32_e32 v156, 0, v122
	v_max_f32_e32 v157, 0, v123
	v_pk_mul_f32 v[246:247], v[56:57], v[246:247]
	v_pk_mul_f32 v[158:159], v[160:161], v[158:159]
	v_pk_fma_f32 v[56:57], v[212:213], v[246:247], v[238:239] neg_lo:[1,0,0] neg_hi:[1,0,0]
	v_pk_fma_f32 v[160:161], v[58:59], v[158:159], v[156:157] neg_lo:[1,0,0] neg_hi:[1,0,0]
	v_pk_mul_f32 v[246:247], v[56:57], v[108:109]
	v_pk_mul_f32 v[158:159], v[160:161], v[110:111]
	v_cvt_pk_bf16_f32 v50, v246, v247
	v_cvt_pk_bf16_f32 v51, v158, v159
	v_add_u32_e32 v235, 1, v227
	v_add_u32_e32 v245, 2, v228
	v_cmp_gt_u32_e64 s[38:39], s64, v235
	v_cmp_gt_u32_e32 vcc, s88, v245
	v_add_u32_e32 v235, 11264, v230
	s_and_b64 s[38:39], s[38:39], vcc
	s_and_saveexec_b64 s[30:31], s[38:39]
	global_store_dwordx4 v235, v[48:51], s[50:51]
	s_mov_b64 exec, s[30:31]
	s_nop 1
	v_add_u32_e32 v235, 3, v228
	v_cmp_gt_i32_e32 vcc, 0x4000, v235
	s_nop 1
	v_cndmask_b32_e32 v245, v222, v221, vcc
	v_and_b32_e32 v235, v235, v245
	v_cmp_eq_u32_e64 s[34:35], 0, v235
	v_cmp_eq_u32_e64 s[36:37], v235, v245
	s_nop 1
	v_cndmask_b32_e64 v104, v104, 0, s[34:35]
	v_cndmask_b32_e64 v105, v105, 0, s[34:35]
	v_cndmask_b32_e64 v106, v106, 0, s[34:35]
	v_cndmask_b32_e64 v107, v107, 0, s[34:35]
	v_cndmask_b32_e64 v96, v96, 0, s[34:35]
	v_cndmask_b32_e64 v97, v97, 0, s[34:35]
	v_cndmask_b32_e64 v98, v98, 0, s[34:35]
	v_cndmask_b32_e64 v99, v99, 0, s[34:35]
	v_pk_fma_f32 v[104:105], v[4:5], v[104:105], v[112:113]
	v_pk_fma_f32 v[106:107], v[6:7], v[106:107], v[114:115]
	v_pk_fma_f32 v[96:97], v[32:33], v[96:97], v[152:153]
	v_pk_fma_f32 v[98:99], v[34:35], v[98:99], v[154:155]
	v_pk_fma_f32 v[104:105], v[16:17], v[68:69], v[104:105]
	v_pk_fma_f32 v[106:107], v[18:19], v[70:71], v[106:107]
	v_pk_fma_f32 v[96:97], v[20:21], v[80:81], v[96:97]
	v_pk_fma_f32 v[98:99], v[22:23], v[82:83], v[98:99]
	s_mov_b64 s[30:31], exec
	s_andn2_b64 exec, exec, s[36:37]
	v_pk_fma_f32 v[104:105], v[92:93], v[60:61], v[104:105]
	v_pk_fma_f32 v[106:107], v[94:95], v[62:63], v[106:107]
	v_pk_fma_f32 v[96:97], v[100:101], v[124:125], v[96:97]
	v_pk_fma_f32 v[98:99], v[102:103], v[126:127], v[98:99]
	s_mov_b64 exec, s[30:31]
	v_and_b32_e32 v212, 0x7fffffff, v104
	v_and_b32_e32 v213, 0x7fffffff, v105
	v_and_b32_e32 v50, 0x7fffffff, v106
	v_and_b32_e32 v51, 0x7fffffff, v107
	v_pk_fma_f32 v[238:239], v[212:213], s[90:91], 1.0 op_sel_hi:[1,0,0]
	v_pk_fma_f32 v[56:57], v[50:51], s[90:91], 1.0 op_sel_hi:[1,0,0]
	v_pk_mul_f32 v[48:49], v[104:105], v[104:105]
	v_pk_mul_f32 v[108:109], v[106:107], v[106:107]
	v_rcp_f32_e32 v238, v238
	v_rcp_f32_e32 v239, v239
	v_rcp_f32_e32 v56, v56
	v_rcp_f32_e32 v57, v57
	v_pk_mul_f32 v[48:49], v[48:49], s[44:45] op_sel_hi:[1,0]
	v_pk_mul_f32 v[108:109], v[108:109], s[44:45] op_sel_hi:[1,0]
	v_pk_fma_f32 v[246:247], v[238:239], s[92:93], v[236:237] op_sel_hi:[1,0,0]
	v_pk_fma_f32 v[58:59], v[56:57], s[92:93], v[236:237] op_sel_hi:[1,0,0]
	v_exp_f32_e32 v48, v48
	v_exp_f32_e32 v49, v49
	v_exp_f32_e32 v108, v108
	v_exp_f32_e32 v109, v109
	v_pk_fma_f32 v[246:247], v[238:239], v[246:247], s[96:97] op_sel_hi:[1,1,0]
	v_pk_fma_f32 v[58:59], v[56:57], v[58:59], s[96:97] op_sel_hi:[1,1,0]
	v_pk_fma_f32 v[246:247], v[238:239], v[246:247], s[0:1] op_sel_hi:[1,1,0]
	v_pk_fma_f32 v[58:59], v[56:57], v[58:59], s[0:1] op_sel_hi:[1,1,0]
	v_pk_fma_f32 v[246:247], v[238:239], v[246:247], s[4:5] op_sel_hi:[1,1,0]
	v_pk_fma_f32 v[58:59], v[56:57], v[58:59], s[4:5] op_sel_hi:[1,1,0]
	v_pk_mul_f32 v[246:247], v[238:239], v[246:247]
	v_pk_mul_f32 v[58:59], v[56:57], v[58:59]
	v_max_f32_e32 v238, 0, v104
	v_max_f32_e32 v239, 0, v105
	v_max_f32_e32 v56, 0, v106
	v_max_f32_e32 v57, 0, v107
	v_pk_mul_f32 v[246:247], v[48:49], v[246:247]
	v_pk_mul_f32 v[58:59], v[108:109], v[58:59]
	v_pk_fma_f32 v[48:49], v[212:213], v[246:247], v[238:239] neg_lo:[1,0,0] neg_hi:[1,0,0]
	v_pk_fma_f32 v[108:109], v[50:51], v[58:59], v[56:57] neg_lo:[1,0,0] neg_hi:[1,0,0]
	v_pk_mul_f32 v[246:247], v[48:49], v[96:97]
	v_pk_mul_f32 v[58:59], v[108:109], v[98:99]
	v_cvt_pk_bf16_f32 v54, v246, v247
	v_cvt_pk_bf16_f32 v55, v58, v59
	v_add_u32_e32 v235, 2, v227
	v_add_u32_e32 v245, 3, v228
	v_cmp_gt_u32_e64 s[38:39], s64, v235
	v_cmp_gt_u32_e32 vcc, s88, v245
	v_add_u32_e32 v235, 16896, v230
	s_and_b64 s[38:39], s[38:39], vcc
	s_and_saveexec_b64 s[30:31], s[38:39]
	global_store_dwordx4 v235, v[52:55], s[50:51]
	s_mov_b64 exec, s[30:31]
	s_nop 1
	s_waitcnt lgkmcnt(0)
	v_mov_b32_dpp v12, v0 row_shr:1 row_mask:0xf bank_mask:0xf
	v_mov_b32_dpp v13, v1 row_shr:1 row_mask:0xf bank_mask:0xf
	v_mov_b32_dpp v14, v2 row_shr:1 row_mask:0xf bank_mask:0xf
	v_mov_b32_dpp v15, v3 row_shr:1 row_mask:0xf bank_mask:0xf
	v_mov_b32_dpp v24, v128 row_shr:1 row_mask:0xf bank_mask:0xf
	v_mov_b32_dpp v25, v129 row_shr:1 row_mask:0xf bank_mask:0xf
	v_mov_b32_dpp v26, v130 row_shr:1 row_mask:0xf bank_mask:0xf
	v_mov_b32_dpp v27, v131 row_shr:1 row_mask:0xf bank_mask:0xf
	v_mov_b32_dpp v28, v8 row_shl:1 row_mask:0xf bank_mask:0xf
	v_mov_b32_dpp v29, v9 row_shl:1 row_mask:0xf bank_mask:0xf
	v_mov_b32_dpp v30, v10 row_shl:1 row_mask:0xf bank_mask:0xf
	v_mov_b32_dpp v31, v11 row_shl:1 row_mask:0xf bank_mask:0xf
	v_mov_b32_dpp v40, v36 row_shl:1 row_mask:0xf bank_mask:0xf
	v_mov_b32_dpp v41, v37 row_shl:1 row_mask:0xf bank_mask:0xf
	v_mov_b32_dpp v42, v38 row_shl:1 row_mask:0xf bank_mask:0xf
	v_mov_b32_dpp v43, v39 row_shl:1 row_mask:0xf bank_mask:0xf
	v_add_u32_e32 v235, 128, v228
	v_cmp_gt_i32_e32 vcc, 0x4000, v235
	s_nop 1
	v_cndmask_b32_e32 v245, v222, v221, vcc
	v_and_b32_e32 v235, v235, v245
	v_cmp_eq_u32_e64 s[34:35], 0, v235
	v_cmp_eq_u32_e64 s[36:37], v235, v245
	s_nop 1
	v_cndmask_b32_e64 v12, v12, 0, s[34:35]
	v_cndmask_b32_e64 v13, v13, 0, s[34:35]
	v_cndmask_b32_e64 v14, v14, 0, s[34:35]
	v_cndmask_b32_e64 v15, v15, 0, s[34:35]
	v_cndmask_b32_e64 v24, v24, 0, s[34:35]
	v_cndmask_b32_e64 v25, v25, 0, s[34:35]
	v_cndmask_b32_e64 v26, v26, 0, s[34:35]
	v_cndmask_b32_e64 v27, v27, 0, s[34:35]
	v_pk_fma_f32 v[12:13], v[4:5], v[12:13], v[112:113]
	v_pk_fma_f32 v[14:15], v[6:7], v[14:15], v[114:115]
	v_pk_fma_f32 v[24:25], v[32:33], v[24:25], v[152:153]
	v_pk_fma_f32 v[26:27], v[34:35], v[26:27], v[154:155]
	v_pk_fma_f32 v[12:13], v[8:9], v[68:69], v[12:13]
	v_pk_fma_f32 v[14:15], v[10:11], v[70:71], v[14:15]
	v_pk_fma_f32 v[24:25], v[36:37], v[80:81], v[24:25]
	v_pk_fma_f32 v[26:27], v[38:39], v[82:83], v[26:27]
	s_mov_b64 s[30:31], exec
	s_andn2_b64 exec, exec, s[36:37]
	v_pk_fma_f32 v[12:13], v[92:93], v[88:89], v[12:13]
	v_pk_fma_f32 v[14:15], v[94:95], v[90:91], v[14:15]
	v_pk_fma_f32 v[24:25], v[100:101], v[76:77], v[24:25]
	v_pk_fma_f32 v[26:27], v[102:103], v[78:79], v[26:27]
	s_mov_b64 exec, s[30:31]
	v_and_b32_e32 v212, 0x7fffffff, v12
	v_and_b32_e32 v213, 0x7fffffff, v13
	v_and_b32_e32 v18, 0x7fffffff, v14
	v_and_b32_e32 v19, 0x7fffffff, v15
	v_pk_fma_f32 v[238:239], v[212:213], s[90:91], 1.0 op_sel_hi:[1,0,0]
	v_pk_fma_f32 v[20:21], v[18:19], s[90:91], 1.0 op_sel_hi:[1,0,0]
	v_pk_mul_f32 v[16:17], v[12:13], v[12:13]
	v_pk_mul_f32 v[48:49], v[14:15], v[14:15]
	v_rcp_f32_e32 v238, v238
	v_rcp_f32_e32 v239, v239
	v_rcp_f32_e32 v20, v20
	v_rcp_f32_e32 v21, v21
	v_pk_mul_f32 v[16:17], v[16:17], s[44:45] op_sel_hi:[1,0]
	v_pk_mul_f32 v[48:49], v[48:49], s[44:45] op_sel_hi:[1,0]
	v_pk_fma_f32 v[246:247], v[238:239], s[92:93], v[236:237] op_sel_hi:[1,0,0]
	v_pk_fma_f32 v[22:23], v[20:21], s[92:93], v[236:237] op_sel_hi:[1,0,0]
	v_exp_f32_e32 v16, v16
	v_exp_f32_e32 v17, v17
	v_exp_f32_e32 v48, v48
	v_exp_f32_e32 v49, v49
	v_pk_fma_f32 v[246:247], v[238:239], v[246:247], s[96:97] op_sel_hi:[1,1,0]
	v_pk_fma_f32 v[22:23], v[20:21], v[22:23], s[96:97] op_sel_hi:[1,1,0]
	v_pk_fma_f32 v[246:247], v[238:239], v[246:247], s[0:1] op_sel_hi:[1,1,0]
	v_pk_fma_f32 v[22:23], v[20:21], v[22:23], s[0:1] op_sel_hi:[1,1,0]
	v_pk_fma_f32 v[246:247], v[238:239], v[246:247], s[4:5] op_sel_hi:[1,1,0]
	v_pk_fma_f32 v[22:23], v[20:21], v[22:23], s[4:5] op_sel_hi:[1,1,0]
	v_pk_mul_f32 v[246:247], v[238:239], v[246:247]
	v_pk_mul_f32 v[22:23], v[20:21], v[22:23]
	v_max_f32_e32 v238, 0, v12
	v_max_f32_e32 v239, 0, v13
	v_max_f32_e32 v20, 0, v14
	v_max_f32_e32 v21, 0, v15
	v_pk_mul_f32 v[246:247], v[16:17], v[246:247]
	v_pk_mul_f32 v[22:23], v[48:49], v[22:23]
	v_pk_fma_f32 v[16:17], v[212:213], v[246:247], v[238:239] neg_lo:[1,0,0] neg_hi:[1,0,0]
	v_pk_fma_f32 v[48:49], v[18:19], v[22:23], v[20:21] neg_lo:[1,0,0] neg_hi:[1,0,0]
	v_pk_mul_f32 v[246:247], v[16:17], v[24:25]
	v_pk_mul_f32 v[22:23], v[48:49], v[26:27]
	v_cvt_pk_bf16_f32 v118, v246, v247
	v_cvt_pk_bf16_f32 v119, v22, v23
	v_add_u32_e32 v235, 127, v227
	v_add_u32_e32 v245, 128, v228
	v_cmp_gt_u32_e64 s[38:39], s64, v235
	v_cmp_gt_u32_e32 vcc, s88, v245
	v_add_u32_e32 v235, 720896, v230
	s_and_b64 s[38:39], s[38:39], vcc
	s_and_saveexec_b64 s[30:31], s[38:39]
	global_store_dwordx4 v235, v[116:119], s[50:51]
	s_mov_b64 exec, s[30:31]
	s_nop 1
	v_add_u32_e32 v235, 129, v228
	v_cmp_gt_i32_e32 vcc, 0x4000, v235
	s_nop 1
	v_cndmask_b32_e32 v245, v222, v221, vcc
	v_and_b32_e32 v235, v235, v245
	v_cmp_eq_u32_e64 s[34:35], 0, v235
	v_cmp_eq_u32_e64 s[36:37], v235, v245
	s_nop 1
	v_cndmask_b32_e64 v8, v8, 0, s[34:35]
	v_cndmask_b32_e64 v9, v9, 0, s[34:35]
	v_cndmask_b32_e64 v10, v10, 0, s[34:35]
	v_cndmask_b32_e64 v11, v11, 0, s[34:35]
	v_cndmask_b32_e64 v36, v36, 0, s[34:35]
	v_cndmask_b32_e64 v37, v37, 0, s[34:35]
	v_cndmask_b32_e64 v38, v38, 0, s[34:35]
	v_cndmask_b32_e64 v39, v39, 0, s[34:35]
	v_pk_fma_f32 v[8:9], v[4:5], v[8:9], v[112:113]
	v_pk_fma_f32 v[10:11], v[6:7], v[10:11], v[114:115]
	v_pk_fma_f32 v[36:37], v[32:33], v[36:37], v[152:153]
	v_pk_fma_f32 v[38:39], v[34:35], v[38:39], v[154:155]
	v_pk_fma_f32 v[8:9], v[88:89], v[68:69], v[8:9]
	v_pk_fma_f32 v[10:11], v[90:91], v[70:71], v[10:11]
	v_pk_fma_f32 v[36:37], v[76:77], v[80:81], v[36:37]
	v_pk_fma_f32 v[38:39], v[78:79], v[82:83], v[38:39]
	s_mov_b64 s[30:31], exec
	s_andn2_b64 exec, exec, s[36:37]
	v_pk_fma_f32 v[8:9], v[92:93], v[72:73], v[8:9]
	v_pk_fma_f32 v[10:11], v[94:95], v[74:75], v[10:11]
	v_pk_fma_f32 v[36:37], v[100:101], v[64:65], v[36:37]
	v_pk_fma_f32 v[38:39], v[102:103], v[66:67], v[38:39]
	s_mov_b64 exec, s[30:31]
	v_and_b32_e32 v212, 0x7fffffff, v8
	v_and_b32_e32 v213, 0x7fffffff, v9
	v_and_b32_e32 v14, 0x7fffffff, v10
	v_and_b32_e32 v15, 0x7fffffff, v11
	v_pk_fma_f32 v[238:239], v[212:213], s[90:91], 1.0 op_sel_hi:[1,0,0]
	v_pk_fma_f32 v[16:17], v[14:15], s[90:91], 1.0 op_sel_hi:[1,0,0]
	v_pk_mul_f32 v[12:13], v[8:9], v[8:9]
	v_pk_mul_f32 v[20:21], v[10:11], v[10:11]
	v_rcp_f32_e32 v238, v238
	v_rcp_f32_e32 v239, v239
	v_rcp_f32_e32 v16, v16
	v_rcp_f32_e32 v17, v17
	v_pk_mul_f32 v[12:13], v[12:13], s[44:45] op_sel_hi:[1,0]
	v_pk_mul_f32 v[20:21], v[20:21], s[44:45] op_sel_hi:[1,0]
	v_pk_fma_f32 v[246:247], v[238:239], s[92:93], v[236:237] op_sel_hi:[1,0,0]
	v_pk_fma_f32 v[18:19], v[16:17], s[92:93], v[236:237] op_sel_hi:[1,0,0]
	v_exp_f32_e32 v12, v12
	v_exp_f32_e32 v13, v13
	v_exp_f32_e32 v20, v20
	v_exp_f32_e32 v21, v21
	v_pk_fma_f32 v[246:247], v[238:239], v[246:247], s[96:97] op_sel_hi:[1,1,0]
	v_pk_fma_f32 v[18:19], v[16:17], v[18:19], s[96:97] op_sel_hi:[1,1,0]
	v_pk_fma_f32 v[246:247], v[238:239], v[246:247], s[0:1] op_sel_hi:[1,1,0]
	v_pk_fma_f32 v[18:19], v[16:17], v[18:19], s[0:1] op_sel_hi:[1,1,0]
	v_pk_fma_f32 v[246:247], v[238:239], v[246:247], s[4:5] op_sel_hi:[1,1,0]
	v_pk_fma_f32 v[18:19], v[16:17], v[18:19], s[4:5] op_sel_hi:[1,1,0]
	v_pk_mul_f32 v[246:247], v[238:239], v[246:247]
	v_pk_mul_f32 v[18:19], v[16:17], v[18:19]
	v_max_f32_e32 v238, 0, v8
	v_max_f32_e32 v239, 0, v9
	v_max_f32_e32 v16, 0, v10
	v_max_f32_e32 v17, 0, v11
	v_pk_mul_f32 v[246:247], v[12:13], v[246:247]
	v_pk_mul_f32 v[18:19], v[20:21], v[18:19]
	v_pk_fma_f32 v[12:13], v[212:213], v[246:247], v[238:239] neg_lo:[1,0,0] neg_hi:[1,0,0]
	v_pk_fma_f32 v[20:21], v[14:15], v[18:19], v[16:17] neg_lo:[1,0,0] neg_hi:[1,0,0]
	v_pk_mul_f32 v[246:247], v[12:13], v[36:37]
	v_pk_mul_f32 v[18:19], v[20:21], v[38:39]
	v_cvt_pk_bf16_f32 v46, v246, v247
	v_cvt_pk_bf16_f32 v47, v18, v19
	v_add_u32_e32 v235, 128, v227
	v_add_u32_e32 v245, 129, v228
	v_cmp_gt_u32_e64 s[38:39], s64, v235
	v_cmp_gt_u32_e32 vcc, s88, v245
	v_add_u32_e32 v235, 726528, v230
	s_and_b64 s[38:39], s[38:39], vcc
	s_and_saveexec_b64 s[30:31], s[38:39]
	global_store_dwordx4 v235, v[44:47], s[50:51]
	s_mov_b64 exec, s[30:31]
	s_nop 1
	v_add_u32_e32 v235, 130, v228
	v_cmp_gt_i32_e32 vcc, 0x4000, v235
	s_nop 1
	v_cndmask_b32_e32 v245, v222, v221, vcc
	v_and_b32_e32 v235, v235, v245
	v_cmp_eq_u32_e64 s[34:35], 0, v235
	v_cmp_eq_u32_e64 s[36:37], v235, v245
	s_nop 1
	v_cndmask_b32_e64 v88, v88, 0, s[34:35]
	v_cndmask_b32_e64 v89, v89, 0, s[34:35]
	v_cndmask_b32_e64 v90, v90, 0, s[34:35]
	v_cndmask_b32_e64 v91, v91, 0, s[34:35]
	v_cndmask_b32_e64 v76, v76, 0, s[34:35]
	v_cndmask_b32_e64 v77, v77, 0, s[34:35]
	v_cndmask_b32_e64 v78, v78, 0, s[34:35]
	v_cndmask_b32_e64 v79, v79, 0, s[34:35]
	v_pk_fma_f32 v[88:89], v[4:5], v[88:89], v[112:113]
	v_pk_fma_f32 v[90:91], v[6:7], v[90:91], v[114:115]
	v_pk_fma_f32 v[76:77], v[32:33], v[76:77], v[152:153]
	v_pk_fma_f32 v[78:79], v[34:35], v[78:79], v[154:155]
	v_pk_fma_f32 v[88:89], v[72:73], v[68:69], v[88:89]
	v_pk_fma_f32 v[90:91], v[74:75], v[70:71], v[90:91]
	v_pk_fma_f32 v[76:77], v[64:65], v[80:81], v[76:77]
	v_pk_fma_f32 v[78:79], v[66:67], v[82:83], v[78:79]
	s_mov_b64 s[30:31], exec
	s_andn2_b64 exec, exec, s[36:37]
	v_pk_fma_f32 v[88:89], v[92:93], v[0:1], v[88:89]
	v_pk_fma_f32 v[90:91], v[94:95], v[2:3], v[90:91]
	v_pk_fma_f32 v[76:77], v[100:101], v[128:129], v[76:77]
	v_pk_fma_f32 v[78:79], v[102:103], v[130:131], v[78:79]
	s_mov_b64 exec, s[30:31]
	v_and_b32_e32 v212, 0x7fffffff, v88
	v_and_b32_e32 v213, 0x7fffffff, v89
	v_and_b32_e32 v10, 0x7fffffff, v90
	v_and_b32_e32 v11, 0x7fffffff, v91
	v_pk_fma_f32 v[238:239], v[212:213], s[90:91], 1.0 op_sel_hi:[1,0,0]
	v_pk_fma_f32 v[12:13], v[10:11], s[90:91], 1.0 op_sel_hi:[1,0,0]
	v_pk_mul_f32 v[8:9], v[88:89], v[88:89]
	v_pk_mul_f32 v[16:17], v[90:91], v[90:91]
	v_rcp_f32_e32 v238, v238
	v_rcp_f32_e32 v239, v239
	v_rcp_f32_e32 v12, v12
	v_rcp_f32_e32 v13, v13
	v_pk_mul_f32 v[8:9], v[8:9], s[44:45] op_sel_hi:[1,0]
	v_pk_mul_f32 v[16:17], v[16:17], s[44:45] op_sel_hi:[1,0]
	v_pk_fma_f32 v[246:247], v[238:239], s[92:93], v[236:237] op_sel_hi:[1,0,0]
	v_pk_fma_f32 v[14:15], v[12:13], s[92:93], v[236:237] op_sel_hi:[1,0,0]
	v_exp_f32_e32 v8, v8
	v_exp_f32_e32 v9, v9
	v_exp_f32_e32 v16, v16
	v_exp_f32_e32 v17, v17
	v_pk_fma_f32 v[246:247], v[238:239], v[246:247], s[96:97] op_sel_hi:[1,1,0]
	v_pk_fma_f32 v[14:15], v[12:13], v[14:15], s[96:97] op_sel_hi:[1,1,0]
	v_pk_fma_f32 v[246:247], v[238:239], v[246:247], s[0:1] op_sel_hi:[1,1,0]
	v_pk_fma_f32 v[14:15], v[12:13], v[14:15], s[0:1] op_sel_hi:[1,1,0]
	v_pk_fma_f32 v[246:247], v[238:239], v[246:247], s[4:5] op_sel_hi:[1,1,0]
	v_pk_fma_f32 v[14:15], v[12:13], v[14:15], s[4:5] op_sel_hi:[1,1,0]
	v_pk_mul_f32 v[246:247], v[238:239], v[246:247]
	v_pk_mul_f32 v[14:15], v[12:13], v[14:15]
	v_max_f32_e32 v238, 0, v88
	v_max_f32_e32 v239, 0, v89
	v_max_f32_e32 v12, 0, v90
	v_max_f32_e32 v13, 0, v91
	v_pk_mul_f32 v[246:247], v[8:9], v[246:247]
	v_pk_mul_f32 v[14:15], v[16:17], v[14:15]
	v_pk_fma_f32 v[8:9], v[212:213], v[246:247], v[238:239] neg_lo:[1,0,0] neg_hi:[1,0,0]
	v_pk_fma_f32 v[16:17], v[10:11], v[14:15], v[12:13] neg_lo:[1,0,0] neg_hi:[1,0,0]
	v_pk_mul_f32 v[246:247], v[8:9], v[76:77]
	v_pk_mul_f32 v[14:15], v[16:17], v[78:79]
	v_cvt_pk_bf16_f32 v134, v246, v247
	v_cvt_pk_bf16_f32 v135, v14, v15
	v_add_u32_e32 v235, 129, v227
	v_add_u32_e32 v245, 130, v228
	v_cmp_gt_u32_e64 s[38:39], s64, v235
	v_cmp_gt_u32_e32 vcc, s88, v245
	v_add_u32_e32 v235, 732160, v230
	s_and_b64 s[38:39], s[38:39], vcc
	s_and_saveexec_b64 s[30:31], s[38:39]
	global_store_dwordx4 v235, v[132:135], s[50:51]
	s_mov_b64 exec, s[30:31]
	s_nop 1
	v_add_u32_e32 v235, 131, v228
	v_cmp_gt_i32_e32 vcc, 0x4000, v235
	s_nop 1
	v_cndmask_b32_e32 v245, v222, v221, vcc
	v_and_b32_e32 v235, v235, v245
	v_cmp_eq_u32_e64 s[34:35], 0, v235
	v_cmp_eq_u32_e64 s[36:37], v235, v245
	s_nop 1
	v_cndmask_b32_e64 v72, v72, 0, s[34:35]
	v_cndmask_b32_e64 v73, v73, 0, s[34:35]
	v_cndmask_b32_e64 v74, v74, 0, s[34:35]
	v_cndmask_b32_e64 v75, v75, 0, s[34:35]
	v_cndmask_b32_e64 v64, v64, 0, s[34:35]
	v_cndmask_b32_e64 v65, v65, 0, s[34:35]
	v_cndmask_b32_e64 v66, v66, 0, s[34:35]
	v_cndmask_b32_e64 v67, v67, 0, s[34:35]
	v_pk_fma_f32 v[72:73], v[4:5], v[72:73], v[112:113]
	v_pk_fma_f32 v[74:75], v[6:7], v[74:75], v[114:115]
	v_pk_fma_f32 v[64:65], v[32:33], v[64:65], v[152:153]
	v_pk_fma_f32 v[66:67], v[34:35], v[66:67], v[154:155]
	v_pk_fma_f32 v[72:73], v[0:1], v[68:69], v[72:73]
	v_pk_fma_f32 v[74:75], v[2:3], v[70:71], v[74:75]
	v_pk_fma_f32 v[64:65], v[128:129], v[80:81], v[64:65]
	v_pk_fma_f32 v[66:67], v[130:131], v[82:83], v[66:67]
	s_mov_b64 s[30:31], exec
	s_andn2_b64 exec, exec, s[36:37]
	v_pk_fma_f32 v[72:73], v[92:93], v[28:29], v[72:73]
	v_pk_fma_f32 v[74:75], v[94:95], v[30:31], v[74:75]
	v_pk_fma_f32 v[64:65], v[100:101], v[40:41], v[64:65]
	v_pk_fma_f32 v[66:67], v[102:103], v[42:43], v[66:67]
	s_mov_b64 exec, s[30:31]
	v_and_b32_e32 v212, 0x7fffffff, v72
	v_and_b32_e32 v213, 0x7fffffff, v73
	v_and_b32_e32 v10, 0x7fffffff, v74
	v_and_b32_e32 v11, 0x7fffffff, v75
	v_pk_fma_f32 v[238:239], v[212:213], s[90:91], 1.0 op_sel_hi:[1,0,0]
	v_pk_fma_f32 v[12:13], v[10:11], s[90:91], 1.0 op_sel_hi:[1,0,0]
	v_pk_mul_f32 v[8:9], v[72:73], v[72:73]
	v_pk_mul_f32 v[16:17], v[74:75], v[74:75]
	v_rcp_f32_e32 v238, v238
	v_rcp_f32_e32 v239, v239
	v_rcp_f32_e32 v12, v12
	v_rcp_f32_e32 v13, v13
	v_pk_mul_f32 v[8:9], v[8:9], s[44:45] op_sel_hi:[1,0]
	v_pk_mul_f32 v[16:17], v[16:17], s[44:45] op_sel_hi:[1,0]
	v_pk_fma_f32 v[246:247], v[238:239], s[92:93], v[236:237] op_sel_hi:[1,0,0]
	v_pk_fma_f32 v[14:15], v[12:13], s[92:93], v[236:237] op_sel_hi:[1,0,0]
	v_exp_f32_e32 v8, v8
	v_exp_f32_e32 v9, v9
	v_exp_f32_e32 v16, v16
	v_exp_f32_e32 v17, v17
	v_pk_fma_f32 v[246:247], v[238:239], v[246:247], s[96:97] op_sel_hi:[1,1,0]
	v_pk_fma_f32 v[14:15], v[12:13], v[14:15], s[96:97] op_sel_hi:[1,1,0]
	v_pk_fma_f32 v[246:247], v[238:239], v[246:247], s[0:1] op_sel_hi:[1,1,0]
	v_pk_fma_f32 v[14:15], v[12:13], v[14:15], s[0:1] op_sel_hi:[1,1,0]
	v_pk_fma_f32 v[246:247], v[238:239], v[246:247], s[4:5] op_sel_hi:[1,1,0]
	v_pk_fma_f32 v[14:15], v[12:13], v[14:15], s[4:5] op_sel_hi:[1,1,0]
	v_pk_mul_f32 v[246:247], v[238:239], v[246:247]
	v_pk_mul_f32 v[14:15], v[12:13], v[14:15]
	v_max_f32_e32 v238, 0, v72
	v_max_f32_e32 v239, 0, v73
	v_max_f32_e32 v12, 0, v74
	v_max_f32_e32 v13, 0, v75
	v_pk_mul_f32 v[246:247], v[8:9], v[246:247]
	v_pk_mul_f32 v[14:15], v[16:17], v[14:15]
	v_pk_fma_f32 v[8:9], v[212:213], v[246:247], v[238:239] neg_lo:[1,0,0] neg_hi:[1,0,0]
	v_pk_fma_f32 v[16:17], v[10:11], v[14:15], v[12:13] neg_lo:[1,0,0] neg_hi:[1,0,0]
	v_pk_mul_f32 v[246:247], v[8:9], v[64:65]
	v_pk_mul_f32 v[14:15], v[16:17], v[66:67]
	v_cvt_pk_bf16_f32 v86, v246, v247
	v_cvt_pk_bf16_f32 v87, v14, v15
	v_add_u32_e32 v235, 130, v227
	v_add_u32_e32 v245, 131, v228
	v_cmp_gt_u32_e64 s[38:39], s64, v235
	v_cmp_gt_u32_e32 vcc, s88, v245
	v_add_u32_e32 v235, 737792, v230
	s_and_b64 s[38:39], s[38:39], vcc
	s_and_saveexec_b64 s[30:31], s[38:39]
	global_store_dwordx4 v235, v[84:87], s[50:51]
	s_mov_b64 exec, s[30:31]
	s_nop 1
